# A/B test: all per-phase s_setprio flips removed from the five GEMM K-loops
# speedup vs baseline: 1.0136x; 1.0120x over previous
; #define PG8_STAGE(bufoff, gbase, voff) do { _Pragma("unroll") for (int _i = 0; _i < 2; ++_i) \
;         __builtin_amdgcn_global_load_lds((const unsigned*)((const char*)(gbase) + (voff)[_i]), (LAS unsigned*)(lds + (bufoff) + ldsw + _i * 8192), 16, 0, 0); } while (0)
; #define PG8_LDA(dst, b, h) do { _Pragma("unroll") for (int m = 0; m < 4; ++m) _Pragma("unroll") for (int k = 0; k < 2; ++k) dst[m][k] = *(const LAS bf16x8*)(lds + PG8_SA(b, h) + aoff + m * 2048 + k * 1024); } while (0)
; #define PG8_LDB(dst, b, h) do { _Pragma("unroll") for (int n = 0; n < 2; ++n) _Pragma("unroll") for (int k = 0; k < 2; ++k) dst[n][k] = *(const LAS bf16x8*)(lds + PG8_SB(b, h) + boff + n * 2048 + k * 1024); } while (0)
; #define PG8_MMA(ai, bj, At, Bt) do { __builtin_amdgcn_s_setprio(1); _Pragma("unroll") for (int m = 0; m < 4; ++m) _Pragma("unroll") for (int n = 0; n < 2; ++n) _Pragma("unroll") for (int k = 0; k < 2; ++k) \
;         acc[ai][bj][m][n] = __builtin_amdgcn_mfma_f32_16x16x32_bf16(Bt[n][k], At[m][k], acc[ai][bj][m][n], 0, 0, 0); __builtin_amdgcn_s_setprio(0); } while (0)
; #define PG8_BAR __builtin_amdgcn_s_barrier()
; template <class Epi, bool ALIGN_EPI = true, bool SP2 = true>
; DI void gemm_phase(LAS unsigned char* lds, const Gemm g, const StaticOrder& S, const Epi& E) {
;     ...
;             const bool last = (t == nt - 2);
;             const char* a1 = cA + (size_t)(t + 1) * kstep;
;             const char* a2 = last ? nA : cA + (size_t)(t + 2) * kstep; const char* b2 = last ? nB : cB + (size_t)(t + 2) * kstep;
;             const char* a3 = a2 + kstep; const char* b3 = b2 + kstep;
;             if (Epi::MID) { if (t == (nt >> 1)) {
;                 if constexpr (ALIGN_EPI) { if (wr == 0) PG8_BAR; }
;                 E.mid(acc, cur, wr, wc, fr, fq);
;                 if constexpr (ALIGN_EPI) { if (wr == 1) PG8_BAR; } } }
;             if constexpr (SP2) {
;             PG8_LDB(B0, 0, 0); PG8_LDB(B1, 0, 1); PG8_SCHED; PG8_LDA(At, 0, 0); PG8_STAGE(PG8_SA(1, 1), a1 + hstepA, voffA);
;             PG8_WAIT_V(8); PG8_WAIT_L(0); PG8_BAR; PG8_MMA(0, 0, At, B0); PG8_MMA(0, 1, At, B1); PG8_BAR; PG8_SCHED;
;             PG8_LDA(At, 0, 1); PG8_STAGE(PG8_SB(0, 0), b2, voffB); PG8_STAGE(PG8_SB(0, 1), b2 + hstepB, voffB); PG8_STAGE(PG8_SA(0, 0), a2, voffA);
;             PG8_WAIT_V(8); PG8_WAIT_L(0); PG8_BAR; PG8_MMA(1, 0, At, B0); PG8_MMA(1, 1, At, B1); PG8_BAR; PG8_SCHED;
.LBB0_261:
	ds_read_b128 v[150:153], v147
	ds_read_b128 v[154:157], v147 offset:1024
	ds_read_b128 v[158:161], v147 offset:2048
	ds_read_b128 v[162:165], v147 offset:3072
	ds_read_b128 v[166:169], v148
	ds_read_b128 v[170:173], v148 offset:1024
	ds_read_b128 v[174:177], v148 offset:2048
	ds_read_b128 v[178:181], v148 offset:3072
	s_add_u32 s46, s34, 0xfff00080
	s_addc_u32 s47, s35, -1
	s_cmp_eq_u32 s78, 60
	s_cselect_b32 s49, s25, s47
	s_cselect_b32 s48, s74, s46
	s_cselect_b32 s47, s23, s77
	s_cselect_b32 s46, s75, s76
	v_lshl_add_u64 v[216:217], s[34:35], 0, v[136:137]
	s_add_i32 m0, s21, 0xc000
	ds_read_b128 v[182:185], v149
	ds_read_b128 v[186:189], v149 offset:1024
	ds_read_b128 v[192:195], v149 offset:2048
	ds_read_b128 v[196:199], v149 offset:3072
	ds_read_b128 v[200:203], v149 offset:4096
	ds_read_b128 v[204:207], v149 offset:5120
	ds_read_b128 v[208:211], v149 offset:6144
	ds_read_b128 v[212:215], v149 offset:7168
	global_load_lds_dwordx4 v[216:217], off
	v_lshl_add_u64 v[216:217], s[34:35], 0, v[138:139]
	s_add_i32 m0, s21, 0xe000
	s_nop 0
	global_load_lds_dwordx4 v[216:217], off
	s_waitcnt vmcnt(8)
	s_waitcnt lgkmcnt(0)
	s_barrier
	s_waitcnt lgkmcnt(0)
	v_mfma_f32_16x16x32_bf16 v[124:127], v[150:153], v[182:185], v[124:127]
	v_mfma_f32_16x16x32_bf16 v[120:123], v[158:161], v[182:185], v[120:123]
	v_mfma_f32_16x16x32_bf16 v[116:119], v[150:153], v[192:195], v[116:119]
	v_mfma_f32_16x16x32_bf16 v[112:115], v[158:161], v[192:195], v[112:115]
	v_mfma_f32_16x16x32_bf16 v[100:103], v[150:153], v[200:203], v[100:103]
	v_mfma_f32_16x16x32_bf16 v[96:99], v[158:161], v[200:203], v[96:99]
	v_mfma_f32_16x16x32_bf16 v[84:87], v[150:153], v[208:211], v[84:87]
	v_mfma_f32_16x16x32_bf16 v[80:83], v[158:161], v[208:211], v[80:83]
	v_mfma_f32_16x16x32_bf16 v[124:127], v[154:157], v[186:189], v[124:127]
	v_mfma_f32_16x16x32_bf16 v[120:123], v[162:165], v[186:189], v[120:123]
	v_mfma_f32_16x16x32_bf16 v[116:119], v[154:157], v[196:199], v[116:119]
	v_mfma_f32_16x16x32_bf16 v[112:115], v[162:165], v[196:199], v[112:115]
	v_mfma_f32_16x16x32_bf16 v[100:103], v[154:157], v[204:207], v[100:103]
	v_mfma_f32_16x16x32_bf16 v[96:99], v[162:165], v[204:207], v[96:99]
	v_mfma_f32_16x16x32_bf16 v[84:87], v[154:157], v[212:215], v[84:87]
	v_mfma_f32_16x16x32_bf16 v[80:83], v[162:165], v[212:215], v[80:83]
	v_mfma_f32_16x16x32_bf16 v[108:111], v[166:169], v[182:185], v[108:111]
	v_mfma_f32_16x16x32_bf16 v[104:107], v[174:177], v[182:185], v[104:107]
	v_mfma_f32_16x16x32_bf16 v[92:95], v[166:169], v[192:195], v[92:95]
	v_mfma_f32_16x16x32_bf16 v[88:91], v[174:177], v[192:195], v[88:91]
	v_mfma_f32_16x16x32_bf16 v[76:79], v[166:169], v[200:203], v[76:79]
	v_mfma_f32_16x16x32_bf16 v[72:75], v[174:177], v[200:203], v[72:75]
	v_mfma_f32_16x16x32_bf16 v[68:71], v[166:169], v[208:211], v[68:71]
	v_mfma_f32_16x16x32_bf16 v[64:67], v[174:177], v[208:211], v[64:67]
	v_mfma_f32_16x16x32_bf16 v[108:111], v[170:173], v[186:189], v[108:111]
	v_mfma_f32_16x16x32_bf16 v[104:107], v[178:181], v[186:189], v[104:107]
	v_mfma_f32_16x16x32_bf16 v[92:95], v[170:173], v[196:199], v[92:95]
	v_mfma_f32_16x16x32_bf16 v[88:91], v[178:181], v[196:199], v[88:91]
	v_mfma_f32_16x16x32_bf16 v[76:79], v[170:173], v[204:207], v[76:79]
	v_mfma_f32_16x16x32_bf16 v[72:75], v[178:181], v[204:207], v[72:75]
	v_mfma_f32_16x16x32_bf16 v[68:71], v[170:173], v[212:215], v[68:71]
	v_mfma_f32_16x16x32_bf16 v[64:67], v[178:181], v[212:215], v[64:67]
	s_barrier
	s_add_i32 s79, s70, s51
	v_lshl_add_u64 v[216:217], s[46:47], 0, v[132:133]
	s_mov_b32 m0, s79
	ds_read_b128 v[182:185], v149 offset:16384
	ds_read_b128 v[186:189], v149 offset:17408
	ds_read_b128 v[192:195], v149 offset:18432
	ds_read_b128 v[196:199], v149 offset:19456
	ds_read_b128 v[200:203], v149 offset:20480
	ds_read_b128 v[204:207], v149 offset:21504
	ds_read_b128 v[208:211], v149 offset:22528
	ds_read_b128 v[212:215], v149 offset:23552
	global_load_lds_dwordx4 v[216:217], off
	s_add_i32 m0, s79, 0x2000
	s_add_u32 s80, s46, 0x100000
	v_lshl_add_u64 v[218:219], s[46:47], 0, v[128:129]
	s_addc_u32 s81, s47, 0
	s_add_i32 s79, s71, s51
	global_load_lds_dwordx4 v[218:219], off
	v_lshl_add_u64 v[220:221], s[80:81], 0, v[132:133]
	s_mov_b32 m0, s79
	v_lshl_add_u64 v[222:223], s[48:49], 0, v[130:131]
	global_load_lds_dwordx4 v[220:221], off
	v_lshl_add_u64 v[220:221], s[80:81], 0, v[128:129]
	s_add_i32 m0, s79, 0x2000
	s_nop 0
	global_load_lds_dwordx4 v[220:221], off
	v_lshl_add_u64 v[220:221], s[48:49], 0, v[134:135]
	s_mov_b32 m0, s21
	s_nop 0
	global_load_lds_dwordx4 v[220:221], off
	s_mov_b32 m0, s62
	s_nop 0
	global_load_lds_dwordx4 v[222:223], off
	s_waitcnt vmcnt(8)
	s_waitcnt lgkmcnt(0)
	s_barrier
; #define PG8_STAGE(bufoff, gbase, voff) do { _Pragma("unroll") for (int _i = 0; _i < 2; ++_i) \
;         __builtin_amdgcn_global_load_lds((const unsigned*)((const char*)(gbase) + (voff)[_i]), (LAS unsigned*)(lds + (bufoff) + ldsw + _i * 8192), 16, 0, 0); } while (0)
; #define PG8_LDA(dst, b, h) do { _Pragma("unroll") for (int m = 0; m < 4; ++m) _Pragma("unroll") for (int k = 0; k < 2; ++k) dst[m][k] = *(const LAS bf16x8*)(lds + PG8_SA(b, h) + aoff + m * 2048 + k * 1024); } while (0)
; #define PG8_LDB(dst, b, h) do { _Pragma("unroll") for (int n = 0; n < 2; ++n) _Pragma("unroll") for (int k = 0; k < 2; ++k) dst[n][k] = *(const LAS bf16x8*)(lds + PG8_SB(b, h) + boff + n * 2048 + k * 1024); } while (0)
; #define PG8_MMA(ai, bj, At, Bt) do { __builtin_amdgcn_s_setprio(1); _Pragma("unroll") for (int m = 0; m < 4; ++m) _Pragma("unroll") for (int n = 0; n < 2; ++n) _Pragma("unroll") for (int k = 0; k < 2; ++k) \
;         acc[ai][bj][m][n] = __builtin_amdgcn_mfma_f32_16x16x32_bf16(Bt[n][k], At[m][k], acc[ai][bj][m][n], 0, 0, 0); __builtin_amdgcn_s_setprio(0); } while (0)
; #define PG8_WAIT_V(n) asm volatile("s_waitcnt vmcnt(" #n ")" ::: "memory")
; #define PG8_WAIT_L(n) asm volatile("s_waitcnt lgkmcnt(" #n ")" ::: "memory")
; #define PG8_BAR __builtin_amdgcn_s_barrier()
; #define PG8_SCHED __builtin_amdgcn_sched_barrier(0)
; template <class Epi, bool ALIGN_EPI = true, bool SP2 = true>
; DI void gemm_phase(LAS unsigned char* lds, const Gemm g, const StaticOrder& S, const Epi& E) {
;     ...
;             PG8_WAIT_V(8); PG8_WAIT_L(0); PG8_BAR; PG8_MMA(1, 0, At, B0); PG8_MMA(1, 1, At, B1); PG8_BAR; PG8_SCHED;
;             PG8_LDB(B0, 1, 0); PG8_LDB(B1, 1, 1); PG8_SCHED; PG8_LDA(At, 1, 0); PG8_STAGE(PG8_SA(0, 1), a2 + hstepA, voffA);
;             PG8_WAIT_V(8); PG8_WAIT_L(0); PG8_BAR; PG8_MMA(0, 0, At, B0); PG8_MMA(0, 1, At, B1); PG8_BAR; PG8_SCHED;
	s_waitcnt lgkmcnt(0)
	v_mfma_f32_16x16x32_bf16 v[60:63], v[150:153], v[182:185], v[60:63]
	v_mfma_f32_16x16x32_bf16 v[56:59], v[158:161], v[182:185], v[56:59]
	v_mfma_f32_16x16x32_bf16 v[52:55], v[150:153], v[192:195], v[52:55]
	v_mfma_f32_16x16x32_bf16 v[48:51], v[158:161], v[192:195], v[48:51]
	v_mfma_f32_16x16x32_bf16 v[36:39], v[150:153], v[200:203], v[36:39]
	v_mfma_f32_16x16x32_bf16 v[32:35], v[158:161], v[200:203], v[32:35]
	v_mfma_f32_16x16x32_bf16 v[20:23], v[150:153], v[208:211], v[20:23]
	v_mfma_f32_16x16x32_bf16 v[16:19], v[158:161], v[208:211], v[16:19]
	v_mfma_f32_16x16x32_bf16 v[60:63], v[154:157], v[186:189], v[60:63]
	v_mfma_f32_16x16x32_bf16 v[56:59], v[162:165], v[186:189], v[56:59]
	v_mfma_f32_16x16x32_bf16 v[52:55], v[154:157], v[196:199], v[52:55]
	v_mfma_f32_16x16x32_bf16 v[48:51], v[162:165], v[196:199], v[48:51]
	v_mfma_f32_16x16x32_bf16 v[36:39], v[154:157], v[204:207], v[36:39]
	v_mfma_f32_16x16x32_bf16 v[32:35], v[162:165], v[204:207], v[32:35]
	v_mfma_f32_16x16x32_bf16 v[20:23], v[154:157], v[212:215], v[20:23]
	v_mfma_f32_16x16x32_bf16 v[16:19], v[162:165], v[212:215], v[16:19]
	v_mfma_f32_16x16x32_bf16 v[44:47], v[166:169], v[182:185], v[44:47]
	v_mfma_f32_16x16x32_bf16 v[40:43], v[174:177], v[182:185], v[40:43]
	v_mfma_f32_16x16x32_bf16 v[28:31], v[166:169], v[192:195], v[28:31]
	v_mfma_f32_16x16x32_bf16 v[24:27], v[174:177], v[192:195], v[24:27]
	v_mfma_f32_16x16x32_bf16 v[12:15], v[166:169], v[200:203], v[12:15]
	v_mfma_f32_16x16x32_bf16 v[8:11], v[174:177], v[200:203], v[8:11]
	v_mfma_f32_16x16x32_bf16 v[4:7], v[166:169], v[208:211], v[4:7]
	v_mfma_f32_16x16x32_bf16 v[0:3], v[174:177], v[208:211], v[0:3]
	v_mfma_f32_16x16x32_bf16 v[44:47], v[170:173], v[186:189], v[44:47]
	v_mfma_f32_16x16x32_bf16 v[40:43], v[178:181], v[186:189], v[40:43]
	v_mfma_f32_16x16x32_bf16 v[28:31], v[170:173], v[196:199], v[28:31]
	v_mfma_f32_16x16x32_bf16 v[24:27], v[178:181], v[196:199], v[24:27]
	v_mfma_f32_16x16x32_bf16 v[12:15], v[170:173], v[204:207], v[12:15]
	v_mfma_f32_16x16x32_bf16 v[8:11], v[178:181], v[204:207], v[8:11]
	v_mfma_f32_16x16x32_bf16 v[4:7], v[170:173], v[212:215], v[4:7]
	v_mfma_f32_16x16x32_bf16 v[0:3], v[178:181], v[212:215], v[0:3]
	s_barrier
	s_add_i32 s79, 0, 0x18000
	s_add_i32 s80, 0, 0x1c000
	v_add_u32_e32 v162, s79, v145
	v_add_u32_e32 v178, s80, v145
	ds_read_b128 v[150:153], v162
	ds_read_b128 v[154:157], v162 offset:1024
	ds_read_b128 v[158:161], v162 offset:2048
	ds_read_b128 v[162:165], v162 offset:3072
	ds_read_b128 v[166:169], v178
	ds_read_b128 v[170:173], v178 offset:1024
	ds_read_b128 v[174:177], v178 offset:2048
	ds_read_b128 v[178:181], v178 offset:3072
	s_add_u32 s48, s48, 0x100000
	s_addc_u32 s49, s49, 0
	s_mov_b32 m0, s63
	v_lshl_add_u64 v[226:227], s[48:49], 0, v[134:135]
	ds_read_b128 v[182:185], v149 offset:32768
	ds_read_b128 v[186:189], v149 offset:33792
	ds_read_b128 v[192:195], v149 offset:34816
	ds_read_b128 v[196:199], v149 offset:35840
	ds_read_b128 v[200:203], v149 offset:36864
	ds_read_b128 v[204:207], v149 offset:37888
	ds_read_b128 v[208:211], v149 offset:38912
	ds_read_b128 v[212:215], v149 offset:39936
	global_load_lds_dwordx4 v[226:227], off
	v_lshl_add_u64 v[226:227], s[48:49], 0, v[130:131]
	s_mov_b32 m0, s64
	s_nop 0
	global_load_lds_dwordx4 v[226:227], off
	s_waitcnt vmcnt(8)
	s_waitcnt lgkmcnt(0)
	s_barrier
	s_waitcnt lgkmcnt(0)
	v_mfma_f32_16x16x32_bf16 v[124:127], v[150:153], v[182:185], v[124:127]
	v_mfma_f32_16x16x32_bf16 v[120:123], v[158:161], v[182:185], v[120:123]
	v_mfma_f32_16x16x32_bf16 v[116:119], v[150:153], v[192:195], v[116:119]
	v_mfma_f32_16x16x32_bf16 v[112:115], v[158:161], v[192:195], v[112:115]
	v_mfma_f32_16x16x32_bf16 v[100:103], v[150:153], v[200:203], v[100:103]
	v_mfma_f32_16x16x32_bf16 v[96:99], v[158:161], v[200:203], v[96:99]
	v_mfma_f32_16x16x32_bf16 v[84:87], v[150:153], v[208:211], v[84:87]
	v_mfma_f32_16x16x32_bf16 v[80:83], v[158:161], v[208:211], v[80:83]
	v_mfma_f32_16x16x32_bf16 v[124:127], v[154:157], v[186:189], v[124:127]
	v_mfma_f32_16x16x32_bf16 v[120:123], v[162:165], v[186:189], v[120:123]
	v_mfma_f32_16x16x32_bf16 v[116:119], v[154:157], v[196:199], v[116:119]
	v_mfma_f32_16x16x32_bf16 v[112:115], v[162:165], v[196:199], v[112:115]
	v_mfma_f32_16x16x32_bf16 v[100:103], v[154:157], v[204:207], v[100:103]
	v_mfma_f32_16x16x32_bf16 v[96:99], v[162:165], v[204:207], v[96:99]
	v_mfma_f32_16x16x32_bf16 v[84:87], v[154:157], v[212:215], v[84:87]
	v_mfma_f32_16x16x32_bf16 v[80:83], v[162:165], v[212:215], v[80:83]
	v_mfma_f32_16x16x32_bf16 v[108:111], v[166:169], v[182:185], v[108:111]
	v_mfma_f32_16x16x32_bf16 v[104:107], v[174:177], v[182:185], v[104:107]
	v_mfma_f32_16x16x32_bf16 v[92:95], v[166:169], v[192:195], v[92:95]
	v_mfma_f32_16x16x32_bf16 v[88:91], v[174:177], v[192:195], v[88:91]
	v_mfma_f32_16x16x32_bf16 v[76:79], v[166:169], v[200:203], v[76:79]
	v_mfma_f32_16x16x32_bf16 v[72:75], v[174:177], v[200:203], v[72:75]
	v_mfma_f32_16x16x32_bf16 v[68:71], v[166:169], v[208:211], v[68:71]
	v_mfma_f32_16x16x32_bf16 v[64:67], v[174:177], v[208:211], v[64:67]
	v_mfma_f32_16x16x32_bf16 v[108:111], v[170:173], v[186:189], v[108:111]
	v_mfma_f32_16x16x32_bf16 v[104:107], v[178:181], v[186:189], v[104:107]
	v_mfma_f32_16x16x32_bf16 v[92:95], v[170:173], v[196:199], v[92:95]
	v_mfma_f32_16x16x32_bf16 v[88:91], v[178:181], v[196:199], v[88:91]
	v_mfma_f32_16x16x32_bf16 v[76:79], v[170:173], v[204:207], v[76:79]
	v_mfma_f32_16x16x32_bf16 v[72:75], v[178:181], v[204:207], v[72:75]
	v_mfma_f32_16x16x32_bf16 v[68:71], v[170:173], v[212:215], v[68:71]
	v_mfma_f32_16x16x32_bf16 v[64:67], v[178:181], v[212:215], v[64:67]
	s_barrier
; #define PG8_STAGE(bufoff, gbase, voff) do { _Pragma("unroll") for (int _i = 0; _i < 2; ++_i) \
;         __builtin_amdgcn_global_load_lds((const unsigned*)((const char*)(gbase) + (voff)[_i]), (LAS unsigned*)(lds + (bufoff) + ldsw + _i * 8192), 16, 0, 0); } while (0)
; #define PG8_LDA(dst, b, h) do { _Pragma("unroll") for (int m = 0; m < 4; ++m) _Pragma("unroll") for (int k = 0; k < 2; ++k) dst[m][k] = *(const LAS bf16x8*)(lds + PG8_SA(b, h) + aoff + m * 2048 + k * 1024); } while (0)
; #define PG8_MMA(ai, bj, At, Bt) do { __builtin_amdgcn_s_setprio(1); _Pragma("unroll") for (int m = 0; m < 4; ++m) _Pragma("unroll") for (int n = 0; n < 2; ++n) _Pragma("unroll") for (int k = 0; k < 2; ++k) \
;         acc[ai][bj][m][n] = __builtin_amdgcn_mfma_f32_16x16x32_bf16(Bt[n][k], At[m][k], acc[ai][bj][m][n], 0, 0, 0); __builtin_amdgcn_s_setprio(0); } while (0)
; #define PG8_WAIT_V(n) asm volatile("s_waitcnt vmcnt(" #n ")" ::: "memory")
; #define PG8_WAIT_L(n) asm volatile("s_waitcnt lgkmcnt(" #n ")" ::: "memory")
; #define PG8_BAR __builtin_amdgcn_s_barrier()
; #define PG8_SCHED __builtin_amdgcn_sched_barrier(0)
; template <class Epi, bool ALIGN_EPI = true, bool SP2 = true>
; DI void gemm_phase(LAS unsigned char* lds, const Gemm g, const StaticOrder& S, const Epi& E) {
;     ...
;             PG8_LDA(At, 1, 1); PG8_STAGE(PG8_SB(1, 0), b3, voffB); PG8_STAGE(PG8_SB(1, 1), b3 + hstepB, voffB); PG8_STAGE(PG8_SA(1, 0), a3, voffA);
;             PG8_WAIT_V(8); PG8_WAIT_L(0); PG8_BAR; PG8_MMA(1, 0, At, B0); PG8_MMA(1, 1, At, B1); PG8_BAR; PG8_SCHED;
;     ...
;         if constexpr (ALIGN_EPI) { if (wr == 0) PG8_BAR; }
	s_add_i32 s48, s79, s51
	v_lshl_add_u64 v[216:217], v[216:217], 0, s[10:11]
	s_mov_b32 m0, s48
	ds_read_b128 v[182:185], v149 offset:49152
	ds_read_b128 v[186:189], v149 offset:50176
	ds_read_b128 v[192:195], v149 offset:51200
	ds_read_b128 v[196:199], v149 offset:52224
	ds_read_b128 v[200:203], v149 offset:53248
	ds_read_b128 v[204:207], v149 offset:54272
	ds_read_b128 v[208:211], v149 offset:55296
	ds_read_b128 v[212:215], v149 offset:56320
	global_load_lds_dwordx4 v[216:217], off
	s_add_i32 m0, s48, 0x2000
	s_add_u32 s46, s46, 0x100080
	v_lshl_add_u64 v[216:217], v[218:219], 0, s[10:11]
	s_addc_u32 s47, s47, 0
	s_add_i32 s48, s80, s51
	global_load_lds_dwordx4 v[216:217], off
	v_lshl_add_u64 v[216:217], s[46:47], 0, v[132:133]
	s_mov_b32 m0, s48
	s_nop 0
	global_load_lds_dwordx4 v[216:217], off
	v_lshl_add_u64 v[216:217], s[46:47], 0, v[128:129]
	s_add_i32 m0, s48, 0x2000
	s_nop 0
	global_load_lds_dwordx4 v[216:217], off
	v_lshl_add_u64 v[216:217], v[220:221], 0, s[10:11]
	s_mov_b32 m0, s66
	s_nop 0
	global_load_lds_dwordx4 v[216:217], off
	v_lshl_add_u64 v[216:217], v[222:223], 0, s[10:11]
	s_mov_b32 m0, s67
	s_nop 0
	global_load_lds_dwordx4 v[216:217], off
	s_waitcnt vmcnt(8)
	s_waitcnt lgkmcnt(0)
	s_barrier
	s_waitcnt lgkmcnt(0)
	v_mfma_f32_16x16x32_bf16 v[60:63], v[150:153], v[182:185], v[60:63]
	v_mfma_f32_16x16x32_bf16 v[56:59], v[158:161], v[182:185], v[56:59]
	v_mfma_f32_16x16x32_bf16 v[52:55], v[150:153], v[192:195], v[52:55]
	v_mfma_f32_16x16x32_bf16 v[48:51], v[158:161], v[192:195], v[48:51]
	v_mfma_f32_16x16x32_bf16 v[36:39], v[150:153], v[200:203], v[36:39]
	v_mfma_f32_16x16x32_bf16 v[32:35], v[158:161], v[200:203], v[32:35]
	v_mfma_f32_16x16x32_bf16 v[20:23], v[150:153], v[208:211], v[20:23]
	v_mfma_f32_16x16x32_bf16 v[16:19], v[158:161], v[208:211], v[16:19]
	v_mfma_f32_16x16x32_bf16 v[60:63], v[154:157], v[186:189], v[60:63]
	v_mfma_f32_16x16x32_bf16 v[56:59], v[162:165], v[186:189], v[56:59]
	v_mfma_f32_16x16x32_bf16 v[52:55], v[154:157], v[196:199], v[52:55]
	v_mfma_f32_16x16x32_bf16 v[48:51], v[162:165], v[196:199], v[48:51]
	v_mfma_f32_16x16x32_bf16 v[36:39], v[154:157], v[204:207], v[36:39]
	v_mfma_f32_16x16x32_bf16 v[32:35], v[162:165], v[204:207], v[32:35]
	v_mfma_f32_16x16x32_bf16 v[20:23], v[154:157], v[212:215], v[20:23]
	v_mfma_f32_16x16x32_bf16 v[16:19], v[162:165], v[212:215], v[16:19]
	v_mfma_f32_16x16x32_bf16 v[44:47], v[166:169], v[182:185], v[44:47]
	v_mfma_f32_16x16x32_bf16 v[40:43], v[174:177], v[182:185], v[40:43]
	v_mfma_f32_16x16x32_bf16 v[28:31], v[166:169], v[192:195], v[28:31]
	v_mfma_f32_16x16x32_bf16 v[24:27], v[174:177], v[192:195], v[24:27]
	v_mfma_f32_16x16x32_bf16 v[12:15], v[166:169], v[200:203], v[12:15]
	v_mfma_f32_16x16x32_bf16 v[8:11], v[174:177], v[200:203], v[8:11]
	v_mfma_f32_16x16x32_bf16 v[4:7], v[166:169], v[208:211], v[4:7]
	v_mfma_f32_16x16x32_bf16 v[0:3], v[174:177], v[208:211], v[0:3]
	v_mfma_f32_16x16x32_bf16 v[44:47], v[170:173], v[186:189], v[44:47]
	v_mfma_f32_16x16x32_bf16 v[40:43], v[178:181], v[186:189], v[40:43]
	v_mfma_f32_16x16x32_bf16 v[28:31], v[170:173], v[196:199], v[28:31]
	v_mfma_f32_16x16x32_bf16 v[24:27], v[178:181], v[196:199], v[24:27]
	v_mfma_f32_16x16x32_bf16 v[12:15], v[170:173], v[204:207], v[12:15]
	v_mfma_f32_16x16x32_bf16 v[8:11], v[178:181], v[204:207], v[8:11]
	v_mfma_f32_16x16x32_bf16 v[4:7], v[170:173], v[212:215], v[4:7]
	v_mfma_f32_16x16x32_bf16 v[0:3], v[178:181], v[212:215], v[0:3]
	s_barrier
	s_add_i32 s78, s78, 2
	s_add_u32 s34, s34, 0x100
	s_addc_u32 s35, s35, 0
	s_add_u32 s76, s76, 0x100
	s_addc_u32 s77, s77, 0
	s_cmp_gt_u32 s78, 61
	s_cbranch_scc0 .LBB0_261
	s_and_b64 vcc, exec, s[18:19]
	s_cbranch_vccz .LBB0_264
	s_barrier

; #define PG8_STAGE(bufoff, gbase, voff) do { _Pragma("unroll") for (int _i = 0; _i < 2; ++_i) \
;         __builtin_amdgcn_global_load_lds((const unsigned*)((const char*)(gbase) + (voff)[_i]), (LAS unsigned*)(lds + (bufoff) + ldsw + _i * 8192), 16, 0, 0); } while (0)
; #define PG8_LDA(dst, b, h) do { _Pragma("unroll") for (int m = 0; m < 4; ++m) _Pragma("unroll") for (int k = 0; k < 2; ++k) dst[m][k] = *(const LAS bf16x8*)(lds + PG8_SA(b, h) + aoff + m * 2048 + k * 1024); } while (0)
; #define PG8_LDB(dst, b, h) do { _Pragma("unroll") for (int n = 0; n < 2; ++n) _Pragma("unroll") for (int k = 0; k < 2; ++k) dst[n][k] = *(const LAS bf16x8*)(lds + PG8_SB(b, h) + boff + n * 2048 + k * 1024); } while (0)
; #define PG8_MMA(ai, bj, At, Bt) do { __builtin_amdgcn_s_setprio(1); _Pragma("unroll") for (int m = 0; m < 4; ++m) _Pragma("unroll") for (int n = 0; n < 2; ++n) _Pragma("unroll") for (int k = 0; k < 2; ++k) \
;         acc[ai][bj][m][n] = __builtin_amdgcn_mfma_f32_16x16x32_bf16(Bt[n][k], At[m][k], acc[ai][bj][m][n], 0, 0, 0); __builtin_amdgcn_s_setprio(0); } while (0)
; #define PG8_BAR __builtin_amdgcn_s_barrier()
; template <class Epi, bool ALIGN_EPI = true, bool SP2 = true>
; DI void gemm_phase(LAS unsigned char* lds, const Gemm g, const StaticOrder& S, const Epi& E) {
;     ...
;             const bool last = (t == nt - 2);
;             const char* a1 = cA + (size_t)(t + 1) * kstep;
;             const char* a2 = last ? nA : cA + (size_t)(t + 2) * kstep; const char* b2 = last ? nB : cB + (size_t)(t + 2) * kstep;
;             const char* a3 = a2 + kstep; const char* b3 = b2 + kstep;
;             if (Epi::MID) { if (t == (nt >> 1)) {
;                 if constexpr (ALIGN_EPI) { if (wr == 0) PG8_BAR; }
;                 E.mid(acc, cur, wr, wc, fr, fq);
;                 if constexpr (ALIGN_EPI) { if (wr == 1) PG8_BAR; } } }
;             if constexpr (SP2) {
;             PG8_LDB(B0, 0, 0); PG8_LDB(B1, 0, 1); PG8_SCHED; PG8_LDA(At, 0, 0); PG8_STAGE(PG8_SA(1, 1), a1 + hstepA, voffA);
;             PG8_WAIT_V(8); PG8_WAIT_L(0); PG8_BAR; PG8_MMA(0, 0, At, B0); PG8_MMA(0, 1, At, B1); PG8_BAR; PG8_SCHED;
;             PG8_LDA(At, 0, 1); PG8_STAGE(PG8_SB(0, 0), b2, voffB); PG8_STAGE(PG8_SB(0, 1), b2 + hstepB, voffB); PG8_STAGE(PG8_SA(0, 0), a2, voffA);
;             PG8_WAIT_V(8); PG8_WAIT_L(0); PG8_BAR; PG8_MMA(1, 0, At, B0); PG8_MMA(1, 1, At, B1); PG8_BAR; PG8_SCHED;
.LBB0_334:
	ds_read_b128 v[162:165], v158
	ds_read_b128 v[166:169], v158 offset:1024
	ds_read_b128 v[170:173], v158 offset:2048
	ds_read_b128 v[174:177], v158 offset:3072
	ds_read_b128 v[178:181], v159
	ds_read_b128 v[182:185], v159 offset:1024
	ds_read_b128 v[186:189], v159 offset:2048
	ds_read_b128 v[192:195], v159 offset:3072
	s_add_u32 s30, s0, 0xffb80080
	s_addc_u32 s31, s1, -1
	s_cmp_eq_u32 s76, 12
	s_cselect_b32 s35, s25, s31
	s_cselect_b32 s34, s24, s30
	s_cselect_b32 s31, s23, s75
	s_cselect_b32 s30, s73, s74
	v_lshl_add_u64 v[230:231], s[0:1], 0, v[136:137]
	s_add_i32 m0, s49, 0xc000
	ds_read_b128 v[196:199], v160
	ds_read_b128 v[200:203], v160 offset:1024
	ds_read_b128 v[204:207], v160 offset:2048
	ds_read_b128 v[208:211], v160 offset:3072
	ds_read_b128 v[212:215], v160 offset:4096
	ds_read_b128 v[216:219], v160 offset:5120
	ds_read_b128 v[220:223], v160 offset:6144
	ds_read_b128 v[226:229], v160 offset:7168
	global_load_lds_dwordx4 v[230:231], off
	v_lshl_add_u64 v[230:231], s[0:1], 0, v[138:139]
	s_add_i32 m0, s49, 0xe000
	s_nop 0
	global_load_lds_dwordx4 v[230:231], off
	s_waitcnt vmcnt(8)
	s_waitcnt lgkmcnt(0)
	s_barrier
	s_waitcnt lgkmcnt(0)
	v_mfma_f32_16x16x32_bf16 v[124:127], v[162:165], v[196:199], v[124:127]
	v_mfma_f32_16x16x32_bf16 v[120:123], v[170:173], v[196:199], v[120:123]
	v_mfma_f32_16x16x32_bf16 v[116:119], v[162:165], v[204:207], v[116:119]
	v_mfma_f32_16x16x32_bf16 v[112:115], v[170:173], v[204:207], v[112:115]
	v_mfma_f32_16x16x32_bf16 v[100:103], v[162:165], v[212:215], v[100:103]
	v_mfma_f32_16x16x32_bf16 v[96:99], v[170:173], v[212:215], v[96:99]
	v_mfma_f32_16x16x32_bf16 v[84:87], v[162:165], v[220:223], v[84:87]
	v_mfma_f32_16x16x32_bf16 v[80:83], v[170:173], v[220:223], v[80:83]
	v_mfma_f32_16x16x32_bf16 v[124:127], v[166:169], v[200:203], v[124:127]
	v_mfma_f32_16x16x32_bf16 v[120:123], v[174:177], v[200:203], v[120:123]
	v_mfma_f32_16x16x32_bf16 v[116:119], v[166:169], v[208:211], v[116:119]
	v_mfma_f32_16x16x32_bf16 v[112:115], v[174:177], v[208:211], v[112:115]
	v_mfma_f32_16x16x32_bf16 v[100:103], v[166:169], v[216:219], v[100:103]
	v_mfma_f32_16x16x32_bf16 v[96:99], v[174:177], v[216:219], v[96:99]
	v_mfma_f32_16x16x32_bf16 v[84:87], v[166:169], v[226:229], v[84:87]
	v_mfma_f32_16x16x32_bf16 v[80:83], v[174:177], v[226:229], v[80:83]
	v_mfma_f32_16x16x32_bf16 v[108:111], v[178:181], v[196:199], v[108:111]
	v_mfma_f32_16x16x32_bf16 v[104:107], v[186:189], v[196:199], v[104:107]
	v_mfma_f32_16x16x32_bf16 v[92:95], v[178:181], v[204:207], v[92:95]
	v_mfma_f32_16x16x32_bf16 v[88:91], v[186:189], v[204:207], v[88:91]
	v_mfma_f32_16x16x32_bf16 v[76:79], v[178:181], v[212:215], v[76:79]
	v_mfma_f32_16x16x32_bf16 v[72:75], v[186:189], v[212:215], v[72:75]
	v_mfma_f32_16x16x32_bf16 v[68:71], v[178:181], v[220:223], v[68:71]
	v_mfma_f32_16x16x32_bf16 v[64:67], v[186:189], v[220:223], v[64:67]
	v_mfma_f32_16x16x32_bf16 v[108:111], v[182:185], v[200:203], v[108:111]
	v_mfma_f32_16x16x32_bf16 v[104:107], v[192:195], v[200:203], v[104:107]
	v_mfma_f32_16x16x32_bf16 v[92:95], v[182:185], v[208:211], v[92:95]
	v_mfma_f32_16x16x32_bf16 v[88:91], v[192:195], v[208:211], v[88:91]
	v_mfma_f32_16x16x32_bf16 v[76:79], v[182:185], v[216:219], v[76:79]
	v_mfma_f32_16x16x32_bf16 v[72:75], v[192:195], v[216:219], v[72:75]
	v_mfma_f32_16x16x32_bf16 v[68:71], v[182:185], v[226:229], v[68:71]
	v_mfma_f32_16x16x32_bf16 v[64:67], v[192:195], v[226:229], v[64:67]
	s_barrier
	s_add_i32 s77, s67, s47
	v_lshl_add_u64 v[230:231], s[30:31], 0, v[134:135]
	s_mov_b32 m0, s77
	ds_read_b128 v[196:199], v160 offset:16384
	ds_read_b128 v[200:203], v160 offset:17408
	ds_read_b128 v[204:207], v160 offset:18432
	ds_read_b128 v[208:211], v160 offset:19456
	ds_read_b128 v[212:215], v160 offset:20480
	ds_read_b128 v[216:219], v160 offset:21504
	ds_read_b128 v[220:223], v160 offset:22528
	ds_read_b128 v[226:229], v160 offset:23552
	global_load_lds_dwordx4 v[230:231], off
	s_add_i32 m0, s77, 0x2000
	s_add_u32 s78, s30, 0x40000
	v_lshl_add_u64 v[232:233], s[30:31], 0, v[132:133]
	s_addc_u32 s79, s31, 0
	s_add_i32 s77, s68, s47
	global_load_lds_dwordx4 v[232:233], off
	v_lshl_add_u64 v[234:235], s[78:79], 0, v[134:135]
	s_mov_b32 m0, s77
	v_lshl_add_u64 v[236:237], s[34:35], 0, v[130:131]
	global_load_lds_dwordx4 v[234:235], off
	v_lshl_add_u64 v[234:235], s[78:79], 0, v[132:133]
	s_add_i32 m0, s77, 0x2000
	s_nop 0
	global_load_lds_dwordx4 v[234:235], off
	v_lshl_add_u64 v[234:235], s[34:35], 0, v[128:129]
	s_mov_b32 m0, s49
	s_nop 0
	global_load_lds_dwordx4 v[234:235], off
	s_mov_b32 m0, s50
	s_nop 0
	global_load_lds_dwordx4 v[236:237], off
	s_waitcnt vmcnt(8)
	s_waitcnt lgkmcnt(0)
	s_barrier
; #define PG8_STAGE(bufoff, gbase, voff) do { _Pragma("unroll") for (int _i = 0; _i < 2; ++_i) \
;         __builtin_amdgcn_global_load_lds((const unsigned*)((const char*)(gbase) + (voff)[_i]), (LAS unsigned*)(lds + (bufoff) + ldsw + _i * 8192), 16, 0, 0); } while (0)
; #define PG8_LDA(dst, b, h) do { _Pragma("unroll") for (int m = 0; m < 4; ++m) _Pragma("unroll") for (int k = 0; k < 2; ++k) dst[m][k] = *(const LAS bf16x8*)(lds + PG8_SA(b, h) + aoff + m * 2048 + k * 1024); } while (0)
; #define PG8_LDB(dst, b, h) do { _Pragma("unroll") for (int n = 0; n < 2; ++n) _Pragma("unroll") for (int k = 0; k < 2; ++k) dst[n][k] = *(const LAS bf16x8*)(lds + PG8_SB(b, h) + boff + n * 2048 + k * 1024); } while (0)
; #define PG8_MMA(ai, bj, At, Bt) do { __builtin_amdgcn_s_setprio(1); _Pragma("unroll") for (int m = 0; m < 4; ++m) _Pragma("unroll") for (int n = 0; n < 2; ++n) _Pragma("unroll") for (int k = 0; k < 2; ++k) \
;         acc[ai][bj][m][n] = __builtin_amdgcn_mfma_f32_16x16x32_bf16(Bt[n][k], At[m][k], acc[ai][bj][m][n], 0, 0, 0); __builtin_amdgcn_s_setprio(0); } while (0)
; #define PG8_WAIT_V(n) asm volatile("s_waitcnt vmcnt(" #n ")" ::: "memory")
; #define PG8_WAIT_L(n) asm volatile("s_waitcnt lgkmcnt(" #n ")" ::: "memory")
; #define PG8_BAR __builtin_amdgcn_s_barrier()
; #define PG8_SCHED __builtin_amdgcn_sched_barrier(0)
; template <class Epi, bool ALIGN_EPI = true, bool SP2 = true>
; DI void gemm_phase(LAS unsigned char* lds, const Gemm g, const StaticOrder& S, const Epi& E) {
;     ...
;             PG8_WAIT_V(8); PG8_WAIT_L(0); PG8_BAR; PG8_MMA(1, 0, At, B0); PG8_MMA(1, 1, At, B1); PG8_BAR; PG8_SCHED;
;             PG8_LDB(B0, 1, 0); PG8_LDB(B1, 1, 1); PG8_SCHED; PG8_LDA(At, 1, 0); PG8_STAGE(PG8_SA(0, 1), a2 + hstepA, voffA);
;             PG8_WAIT_V(8); PG8_WAIT_L(0); PG8_BAR; PG8_MMA(0, 0, At, B0); PG8_MMA(0, 1, At, B1); PG8_BAR; PG8_SCHED;
	s_waitcnt lgkmcnt(0)
	v_mfma_f32_16x16x32_bf16 v[60:63], v[162:165], v[196:199], v[60:63]
	v_mfma_f32_16x16x32_bf16 v[56:59], v[170:173], v[196:199], v[56:59]
	v_mfma_f32_16x16x32_bf16 v[52:55], v[162:165], v[204:207], v[52:55]
	v_mfma_f32_16x16x32_bf16 v[48:51], v[170:173], v[204:207], v[48:51]
	v_mfma_f32_16x16x32_bf16 v[36:39], v[162:165], v[212:215], v[36:39]
	v_mfma_f32_16x16x32_bf16 v[32:35], v[170:173], v[212:215], v[32:35]
	v_mfma_f32_16x16x32_bf16 v[20:23], v[162:165], v[220:223], v[20:23]
	v_mfma_f32_16x16x32_bf16 v[16:19], v[170:173], v[220:223], v[16:19]
	v_mfma_f32_16x16x32_bf16 v[60:63], v[166:169], v[200:203], v[60:63]
	v_mfma_f32_16x16x32_bf16 v[56:59], v[174:177], v[200:203], v[56:59]
	v_mfma_f32_16x16x32_bf16 v[52:55], v[166:169], v[208:211], v[52:55]
	v_mfma_f32_16x16x32_bf16 v[48:51], v[174:177], v[208:211], v[48:51]
	v_mfma_f32_16x16x32_bf16 v[36:39], v[166:169], v[216:219], v[36:39]
	v_mfma_f32_16x16x32_bf16 v[32:35], v[174:177], v[216:219], v[32:35]
	v_mfma_f32_16x16x32_bf16 v[20:23], v[166:169], v[226:229], v[20:23]
	v_mfma_f32_16x16x32_bf16 v[16:19], v[174:177], v[226:229], v[16:19]
	v_mfma_f32_16x16x32_bf16 v[44:47], v[178:181], v[196:199], v[44:47]
	v_mfma_f32_16x16x32_bf16 v[40:43], v[186:189], v[196:199], v[40:43]
	v_mfma_f32_16x16x32_bf16 v[28:31], v[178:181], v[204:207], v[28:31]
	v_mfma_f32_16x16x32_bf16 v[24:27], v[186:189], v[204:207], v[24:27]
	v_mfma_f32_16x16x32_bf16 v[12:15], v[178:181], v[212:215], v[12:15]
	v_mfma_f32_16x16x32_bf16 v[8:11], v[186:189], v[212:215], v[8:11]
	v_mfma_f32_16x16x32_bf16 v[4:7], v[178:181], v[220:223], v[4:7]
	v_mfma_f32_16x16x32_bf16 v[0:3], v[186:189], v[220:223], v[0:3]
	v_mfma_f32_16x16x32_bf16 v[44:47], v[182:185], v[200:203], v[44:47]
	v_mfma_f32_16x16x32_bf16 v[40:43], v[192:195], v[200:203], v[40:43]
	v_mfma_f32_16x16x32_bf16 v[28:31], v[182:185], v[208:211], v[28:31]
	v_mfma_f32_16x16x32_bf16 v[24:27], v[192:195], v[208:211], v[24:27]
	v_mfma_f32_16x16x32_bf16 v[12:15], v[182:185], v[216:219], v[12:15]
	v_mfma_f32_16x16x32_bf16 v[8:11], v[192:195], v[216:219], v[8:11]
	v_mfma_f32_16x16x32_bf16 v[4:7], v[182:185], v[226:229], v[4:7]
	v_mfma_f32_16x16x32_bf16 v[0:3], v[192:195], v[226:229], v[0:3]
	s_barrier
	s_add_i32 s77, 0, 0x18000
	v_add_u32_e32 v161, s77, v156
	s_add_i32 s78, 0, 0x1c000
	ds_read_b128 v[162:165], v161
	ds_read_b128 v[166:169], v161 offset:1024
	ds_read_b128 v[170:173], v161 offset:2048
	ds_read_b128 v[174:177], v161 offset:3072
	v_add_u32_e32 v161, s78, v156
	ds_read_b128 v[178:181], v161
	ds_read_b128 v[182:185], v161 offset:1024
	ds_read_b128 v[186:189], v161 offset:2048
	ds_read_b128 v[192:195], v161 offset:3072
	s_add_u32 s34, s34, 0x480000
	s_addc_u32 s35, s35, 0
	s_mov_b32 m0, s51
	v_lshl_add_u64 v[238:239], s[34:35], 0, v[128:129]
	ds_read_b128 v[196:199], v160 offset:32768
	ds_read_b128 v[200:203], v160 offset:33792
	ds_read_b128 v[204:207], v160 offset:34816
	ds_read_b128 v[208:211], v160 offset:35840
	ds_read_b128 v[212:215], v160 offset:36864
	ds_read_b128 v[216:219], v160 offset:37888
	ds_read_b128 v[220:223], v160 offset:38912
	ds_read_b128 v[226:229], v160 offset:39936
	global_load_lds_dwordx4 v[238:239], off
	v_lshl_add_u64 v[238:239], s[34:35], 0, v[130:131]
	s_mov_b32 m0, s60
	s_nop 0
	global_load_lds_dwordx4 v[238:239], off
	s_waitcnt vmcnt(8)
	s_waitcnt lgkmcnt(0)
	s_barrier
	s_waitcnt lgkmcnt(0)
	v_mfma_f32_16x16x32_bf16 v[124:127], v[162:165], v[196:199], v[124:127]
	v_mfma_f32_16x16x32_bf16 v[120:123], v[170:173], v[196:199], v[120:123]
	v_mfma_f32_16x16x32_bf16 v[116:119], v[162:165], v[204:207], v[116:119]
	v_mfma_f32_16x16x32_bf16 v[112:115], v[170:173], v[204:207], v[112:115]
	v_mfma_f32_16x16x32_bf16 v[100:103], v[162:165], v[212:215], v[100:103]
	v_mfma_f32_16x16x32_bf16 v[96:99], v[170:173], v[212:215], v[96:99]
	v_mfma_f32_16x16x32_bf16 v[84:87], v[162:165], v[220:223], v[84:87]
	v_mfma_f32_16x16x32_bf16 v[80:83], v[170:173], v[220:223], v[80:83]
	v_mfma_f32_16x16x32_bf16 v[124:127], v[166:169], v[200:203], v[124:127]
	v_mfma_f32_16x16x32_bf16 v[120:123], v[174:177], v[200:203], v[120:123]
	v_mfma_f32_16x16x32_bf16 v[116:119], v[166:169], v[208:211], v[116:119]
	v_mfma_f32_16x16x32_bf16 v[112:115], v[174:177], v[208:211], v[112:115]
	v_mfma_f32_16x16x32_bf16 v[100:103], v[166:169], v[216:219], v[100:103]
	v_mfma_f32_16x16x32_bf16 v[96:99], v[174:177], v[216:219], v[96:99]
	v_mfma_f32_16x16x32_bf16 v[84:87], v[166:169], v[226:229], v[84:87]
	v_mfma_f32_16x16x32_bf16 v[80:83], v[174:177], v[226:229], v[80:83]
	v_mfma_f32_16x16x32_bf16 v[108:111], v[178:181], v[196:199], v[108:111]
	v_mfma_f32_16x16x32_bf16 v[104:107], v[186:189], v[196:199], v[104:107]
	v_mfma_f32_16x16x32_bf16 v[92:95], v[178:181], v[204:207], v[92:95]
	v_mfma_f32_16x16x32_bf16 v[88:91], v[186:189], v[204:207], v[88:91]
	v_mfma_f32_16x16x32_bf16 v[76:79], v[178:181], v[212:215], v[76:79]
	v_mfma_f32_16x16x32_bf16 v[72:75], v[186:189], v[212:215], v[72:75]
	v_mfma_f32_16x16x32_bf16 v[68:71], v[178:181], v[220:223], v[68:71]
	v_mfma_f32_16x16x32_bf16 v[64:67], v[186:189], v[220:223], v[64:67]
	v_mfma_f32_16x16x32_bf16 v[108:111], v[182:185], v[200:203], v[108:111]
	v_mfma_f32_16x16x32_bf16 v[104:107], v[192:195], v[200:203], v[104:107]
	v_mfma_f32_16x16x32_bf16 v[92:95], v[182:185], v[208:211], v[92:95]
	v_mfma_f32_16x16x32_bf16 v[88:91], v[192:195], v[208:211], v[88:91]
	v_mfma_f32_16x16x32_bf16 v[76:79], v[182:185], v[216:219], v[76:79]
	v_mfma_f32_16x16x32_bf16 v[72:75], v[192:195], v[216:219], v[72:75]
	v_mfma_f32_16x16x32_bf16 v[68:71], v[182:185], v[226:229], v[68:71]
	v_mfma_f32_16x16x32_bf16 v[64:67], v[192:195], v[226:229], v[64:67]
	s_barrier
; #define PG8_STAGE(bufoff, gbase, voff) do { _Pragma("unroll") for (int _i = 0; _i < 2; ++_i) \
;         __builtin_amdgcn_global_load_lds((const unsigned*)((const char*)(gbase) + (voff)[_i]), (LAS unsigned*)(lds + (bufoff) + ldsw + _i * 8192), 16, 0, 0); } while (0)
; #define PG8_LDA(dst, b, h) do { _Pragma("unroll") for (int m = 0; m < 4; ++m) _Pragma("unroll") for (int k = 0; k < 2; ++k) dst[m][k] = *(const LAS bf16x8*)(lds + PG8_SA(b, h) + aoff + m * 2048 + k * 1024); } while (0)
; #define PG8_MMA(ai, bj, At, Bt) do { __builtin_amdgcn_s_setprio(1); _Pragma("unroll") for (int m = 0; m < 4; ++m) _Pragma("unroll") for (int n = 0; n < 2; ++n) _Pragma("unroll") for (int k = 0; k < 2; ++k) \
;         acc[ai][bj][m][n] = __builtin_amdgcn_mfma_f32_16x16x32_bf16(Bt[n][k], At[m][k], acc[ai][bj][m][n], 0, 0, 0); __builtin_amdgcn_s_setprio(0); } while (0)
; #define PG8_WAIT_V(n) asm volatile("s_waitcnt vmcnt(" #n ")" ::: "memory")
; #define PG8_WAIT_L(n) asm volatile("s_waitcnt lgkmcnt(" #n ")" ::: "memory")
; #define PG8_BAR __builtin_amdgcn_s_barrier()
; #define PG8_SCHED __builtin_amdgcn_sched_barrier(0)
; template <class Epi, bool ALIGN_EPI = true, bool SP2 = true>
; DI void gemm_phase(LAS unsigned char* lds, const Gemm g, const StaticOrder& S, const Epi& E) {
;     ...
;             PG8_LDA(At, 1, 1); PG8_STAGE(PG8_SB(1, 0), b3, voffB); PG8_STAGE(PG8_SB(1, 1), b3 + hstepB, voffB); PG8_STAGE(PG8_SA(1, 0), a3, voffA);
;             PG8_WAIT_V(8); PG8_WAIT_L(0); PG8_BAR; PG8_MMA(1, 0, At, B0); PG8_MMA(1, 1, At, B1); PG8_BAR; PG8_SCHED;
;     ...
;         if constexpr (ALIGN_EPI) { if (wr == 0) PG8_BAR; }
	s_add_i32 s34, s77, s47
	v_lshl_add_u64 v[230:231], v[230:231], 0, s[18:19]
	s_mov_b32 m0, s34
	ds_read_b128 v[196:199], v160 offset:49152
	ds_read_b128 v[200:203], v160 offset:50176
	ds_read_b128 v[204:207], v160 offset:51200
	ds_read_b128 v[208:211], v160 offset:52224
	ds_read_b128 v[212:215], v160 offset:53248
	ds_read_b128 v[216:219], v160 offset:54272
	ds_read_b128 v[220:223], v160 offset:55296
	ds_read_b128 v[226:229], v160 offset:56320
	global_load_lds_dwordx4 v[230:231], off
	s_add_i32 m0, s34, 0x2000
	s_add_u32 s30, s30, 0x40080
	v_lshl_add_u64 v[230:231], v[232:233], 0, s[18:19]
	s_addc_u32 s31, s31, 0
	s_add_i32 s34, s78, s47
	global_load_lds_dwordx4 v[230:231], off
	v_lshl_add_u64 v[230:231], s[30:31], 0, v[134:135]
	s_mov_b32 m0, s34
	s_nop 0
	global_load_lds_dwordx4 v[230:231], off
	v_lshl_add_u64 v[230:231], s[30:31], 0, v[132:133]
	s_add_i32 m0, s34, 0x2000
	s_nop 0
	global_load_lds_dwordx4 v[230:231], off
	v_lshl_add_u64 v[230:231], v[234:235], 0, s[18:19]
	s_mov_b32 m0, s62
	s_nop 0
	global_load_lds_dwordx4 v[230:231], off
	v_lshl_add_u64 v[230:231], v[236:237], 0, s[18:19]
	s_mov_b32 m0, s63
	s_nop 0
	global_load_lds_dwordx4 v[230:231], off
	s_waitcnt vmcnt(8)
	s_waitcnt lgkmcnt(0)
	s_barrier
	s_waitcnt lgkmcnt(0)
	v_mfma_f32_16x16x32_bf16 v[60:63], v[162:165], v[196:199], v[60:63]
	v_mfma_f32_16x16x32_bf16 v[56:59], v[170:173], v[196:199], v[56:59]
	v_mfma_f32_16x16x32_bf16 v[52:55], v[162:165], v[204:207], v[52:55]
	v_mfma_f32_16x16x32_bf16 v[48:51], v[170:173], v[204:207], v[48:51]
	v_mfma_f32_16x16x32_bf16 v[36:39], v[162:165], v[212:215], v[36:39]
	v_mfma_f32_16x16x32_bf16 v[32:35], v[170:173], v[212:215], v[32:35]
	v_mfma_f32_16x16x32_bf16 v[20:23], v[162:165], v[220:223], v[20:23]
	v_mfma_f32_16x16x32_bf16 v[16:19], v[170:173], v[220:223], v[16:19]
	v_mfma_f32_16x16x32_bf16 v[60:63], v[166:169], v[200:203], v[60:63]
	v_mfma_f32_16x16x32_bf16 v[56:59], v[174:177], v[200:203], v[56:59]
	v_mfma_f32_16x16x32_bf16 v[52:55], v[166:169], v[208:211], v[52:55]
	v_mfma_f32_16x16x32_bf16 v[48:51], v[174:177], v[208:211], v[48:51]
	v_mfma_f32_16x16x32_bf16 v[36:39], v[166:169], v[216:219], v[36:39]
	v_mfma_f32_16x16x32_bf16 v[32:35], v[174:177], v[216:219], v[32:35]
	v_mfma_f32_16x16x32_bf16 v[20:23], v[166:169], v[226:229], v[20:23]
	v_mfma_f32_16x16x32_bf16 v[16:19], v[174:177], v[226:229], v[16:19]
	v_mfma_f32_16x16x32_bf16 v[44:47], v[178:181], v[196:199], v[44:47]
	v_mfma_f32_16x16x32_bf16 v[40:43], v[186:189], v[196:199], v[40:43]
	v_mfma_f32_16x16x32_bf16 v[28:31], v[178:181], v[204:207], v[28:31]
	v_mfma_f32_16x16x32_bf16 v[24:27], v[186:189], v[204:207], v[24:27]
	v_mfma_f32_16x16x32_bf16 v[12:15], v[178:181], v[212:215], v[12:15]
	v_mfma_f32_16x16x32_bf16 v[8:11], v[186:189], v[212:215], v[8:11]
	v_mfma_f32_16x16x32_bf16 v[4:7], v[178:181], v[220:223], v[4:7]
	v_mfma_f32_16x16x32_bf16 v[0:3], v[186:189], v[220:223], v[0:3]
	v_mfma_f32_16x16x32_bf16 v[44:47], v[182:185], v[200:203], v[44:47]
	v_mfma_f32_16x16x32_bf16 v[40:43], v[192:195], v[200:203], v[40:43]
	v_mfma_f32_16x16x32_bf16 v[28:31], v[182:185], v[208:211], v[28:31]
	v_mfma_f32_16x16x32_bf16 v[24:27], v[192:195], v[208:211], v[24:27]
	v_mfma_f32_16x16x32_bf16 v[12:15], v[182:185], v[216:219], v[12:15]
	v_mfma_f32_16x16x32_bf16 v[8:11], v[192:195], v[216:219], v[8:11]
	v_mfma_f32_16x16x32_bf16 v[4:7], v[182:185], v[226:229], v[4:7]
	v_mfma_f32_16x16x32_bf16 v[0:3], v[192:195], v[226:229], v[0:3]
	s_barrier
	s_add_i32 s76, s76, 2
	s_add_u32 s0, s0, 0x100
	s_addc_u32 s1, s1, 0
	s_add_u32 s74, s74, 0x100
	s_addc_u32 s75, s75, 0
	s_cmp_gt_u32 s76, 13
	s_cbranch_scc0 .LBB0_334
	s_and_b64 vcc, exec, s[20:21]
	s_cbranch_vccz .LBB0_337
	s_barrier

; #define PG8_STAGE(bufoff, gbase, voff) do { _Pragma("unroll") for (int _i = 0; _i < 2; ++_i) \
;         __builtin_amdgcn_global_load_lds((const unsigned*)((const char*)(gbase) + (voff)[_i]), (LAS unsigned*)(lds + (bufoff) + ldsw + _i * 8192), 16, 0, 0); } while (0)
; #define PG8_LDA(dst, b, h) do { _Pragma("unroll") for (int m = 0; m < 4; ++m) _Pragma("unroll") for (int k = 0; k < 2; ++k) dst[m][k] = *(const LAS bf16x8*)(lds + PG8_SA(b, h) + aoff + m * 2048 + k * 1024); } while (0)
; #define PG8_LDB(dst, b, h) do { _Pragma("unroll") for (int n = 0; n < 2; ++n) _Pragma("unroll") for (int k = 0; k < 2; ++k) dst[n][k] = *(const LAS bf16x8*)(lds + PG8_SB(b, h) + boff + n * 2048 + k * 1024); } while (0)
; #define PG8_MMA(ai, bj, At, Bt) do { __builtin_amdgcn_s_setprio(1); _Pragma("unroll") for (int m = 0; m < 4; ++m) _Pragma("unroll") for (int n = 0; n < 2; ++n) _Pragma("unroll") for (int k = 0; k < 2; ++k) \
;         acc[ai][bj][m][n] = __builtin_amdgcn_mfma_f32_16x16x32_bf16(Bt[n][k], At[m][k], acc[ai][bj][m][n], 0, 0, 0); __builtin_amdgcn_s_setprio(0); } while (0)
; #define PG8_BAR __builtin_amdgcn_s_barrier()
; template <class Epi, bool ALIGN_EPI = true, bool SP2 = true>
; DI void gemm_phase(LAS unsigned char* lds, const Gemm g, const StaticOrder& S, const Epi& E) {
;     ...
;             const bool last = (t == nt - 2);
;             const char* a1 = cA + (size_t)(t + 1) * kstep;
;             const char* a2 = last ? nA : cA + (size_t)(t + 2) * kstep; const char* b2 = last ? nB : cB + (size_t)(t + 2) * kstep;
;             const char* a3 = a2 + kstep; const char* b3 = b2 + kstep;
;             if (Epi::MID) { if (t == (nt >> 1)) {
;                 if constexpr (ALIGN_EPI) { if (wr == 0) PG8_BAR; }
;                 E.mid(acc, cur, wr, wc, fr, fq);
;                 if constexpr (ALIGN_EPI) { if (wr == 1) PG8_BAR; } } }
;             if constexpr (SP2) {
;             PG8_LDB(B0, 0, 0); PG8_LDB(B1, 0, 1); PG8_SCHED; PG8_LDA(At, 0, 0); PG8_STAGE(PG8_SA(1, 1), a1 + hstepA, voffA);
;             PG8_WAIT_V(8); PG8_WAIT_L(0); PG8_BAR; PG8_MMA(0, 0, At, B0); PG8_MMA(0, 1, At, B1); PG8_BAR; PG8_SCHED;
;             PG8_LDA(At, 0, 1); PG8_STAGE(PG8_SB(0, 0), b2, voffB); PG8_STAGE(PG8_SB(0, 1), b2 + hstepB, voffB); PG8_STAGE(PG8_SA(0, 0), a2, voffA);
;             PG8_WAIT_V(8); PG8_WAIT_L(0); PG8_BAR; PG8_MMA(1, 0, At, B0); PG8_MMA(1, 1, At, B1); PG8_BAR; PG8_SCHED;
.LBB0_360:
	ds_read_b128 v[154:157], v144
	ds_read_b128 v[158:161], v144 offset:1024
	ds_read_b128 v[162:165], v144 offset:2048
	ds_read_b128 v[166:169], v144 offset:3072
	ds_read_b128 v[170:173], v145
	ds_read_b128 v[174:177], v145 offset:1024
	ds_read_b128 v[178:181], v145 offset:2048
	ds_read_b128 v[182:185], v145 offset:3072
	s_add_u32 s60, s0, 0xffb80080
	s_addc_u32 s61, s1, -1
	s_cmp_eq_u32 s90, 4
	s_cselect_b32 s63, s49, s61
	s_cselect_b32 s62, s48, s60
	s_cselect_b32 s61, s47, s89
	s_cselect_b32 s60, s87, s88
	v_lshl_add_u64 v[150:151], s[0:1], 0, v[136:137]
	s_add_i32 m0, s69, 0xc000
	ds_read_b128 v[186:189], v148
	ds_read_b128 v[192:195], v148 offset:1024
	ds_read_b128 v[196:199], v148 offset:2048
	ds_read_b128 v[200:203], v148 offset:3072
	ds_read_b128 v[204:207], v148 offset:4096
	ds_read_b128 v[208:211], v148 offset:5120
	ds_read_b128 v[212:215], v148 offset:6144
	ds_read_b128 v[216:219], v148 offset:7168
	global_load_lds_dwordx4 v[150:151], off
	v_lshl_add_u64 v[150:151], s[0:1], 0, v[138:139]
	s_add_i32 m0, s69, 0xe000
	s_nop 0
	global_load_lds_dwordx4 v[150:151], off
	s_waitcnt vmcnt(8)
	s_waitcnt lgkmcnt(0)
	s_barrier
	s_waitcnt lgkmcnt(0)
	v_mfma_f32_16x16x32_bf16 v[124:127], v[154:157], v[186:189], v[124:127]
	v_mfma_f32_16x16x32_bf16 v[120:123], v[162:165], v[186:189], v[120:123]
	v_mfma_f32_16x16x32_bf16 v[116:119], v[154:157], v[196:199], v[116:119]
	v_mfma_f32_16x16x32_bf16 v[112:115], v[162:165], v[196:199], v[112:115]
	v_mfma_f32_16x16x32_bf16 v[100:103], v[154:157], v[204:207], v[100:103]
	v_mfma_f32_16x16x32_bf16 v[96:99], v[162:165], v[204:207], v[96:99]
	v_mfma_f32_16x16x32_bf16 v[84:87], v[154:157], v[212:215], v[84:87]
	v_mfma_f32_16x16x32_bf16 v[80:83], v[162:165], v[212:215], v[80:83]
	v_mfma_f32_16x16x32_bf16 v[124:127], v[158:161], v[192:195], v[124:127]
	v_mfma_f32_16x16x32_bf16 v[120:123], v[166:169], v[192:195], v[120:123]
	v_mfma_f32_16x16x32_bf16 v[116:119], v[158:161], v[200:203], v[116:119]
	v_mfma_f32_16x16x32_bf16 v[112:115], v[166:169], v[200:203], v[112:115]
	v_mfma_f32_16x16x32_bf16 v[100:103], v[158:161], v[208:211], v[100:103]
	v_mfma_f32_16x16x32_bf16 v[96:99], v[166:169], v[208:211], v[96:99]
	v_mfma_f32_16x16x32_bf16 v[84:87], v[158:161], v[216:219], v[84:87]
	v_mfma_f32_16x16x32_bf16 v[80:83], v[166:169], v[216:219], v[80:83]
	v_mfma_f32_16x16x32_bf16 v[108:111], v[170:173], v[186:189], v[108:111]
	v_mfma_f32_16x16x32_bf16 v[104:107], v[178:181], v[186:189], v[104:107]
	v_mfma_f32_16x16x32_bf16 v[92:95], v[170:173], v[196:199], v[92:95]
	v_mfma_f32_16x16x32_bf16 v[88:91], v[178:181], v[196:199], v[88:91]
	v_mfma_f32_16x16x32_bf16 v[76:79], v[170:173], v[204:207], v[76:79]
	v_mfma_f32_16x16x32_bf16 v[72:75], v[178:181], v[204:207], v[72:75]
	v_mfma_f32_16x16x32_bf16 v[68:71], v[170:173], v[212:215], v[68:71]
	v_mfma_f32_16x16x32_bf16 v[64:67], v[178:181], v[212:215], v[64:67]
	v_mfma_f32_16x16x32_bf16 v[108:111], v[174:177], v[192:195], v[108:111]
	v_mfma_f32_16x16x32_bf16 v[104:107], v[182:185], v[192:195], v[104:107]
	v_mfma_f32_16x16x32_bf16 v[92:95], v[174:177], v[200:203], v[92:95]
	v_mfma_f32_16x16x32_bf16 v[88:91], v[182:185], v[200:203], v[88:91]
	v_mfma_f32_16x16x32_bf16 v[76:79], v[174:177], v[208:211], v[76:79]
	v_mfma_f32_16x16x32_bf16 v[72:75], v[182:185], v[208:211], v[72:75]
	v_mfma_f32_16x16x32_bf16 v[68:71], v[174:177], v[216:219], v[68:71]
	v_mfma_f32_16x16x32_bf16 v[64:67], v[182:185], v[216:219], v[64:67]
	s_barrier
	s_add_i32 s91, s78, s68
	v_lshl_add_u64 v[150:151], s[60:61], 0, v[132:133]
	s_mov_b32 m0, s91
	ds_read_b128 v[186:189], v148 offset:16384
	ds_read_b128 v[192:195], v148 offset:17408
	ds_read_b128 v[196:199], v148 offset:18432
	ds_read_b128 v[200:203], v148 offset:19456
	ds_read_b128 v[204:207], v148 offset:20480
	ds_read_b128 v[208:211], v148 offset:21504
	ds_read_b128 v[212:215], v148 offset:22528
	ds_read_b128 v[216:219], v148 offset:23552
	global_load_lds_dwordx4 v[150:151], off
	s_add_i32 m0, s91, 0x2000
	s_add_u32 s92, s60, 0x20000
	v_lshl_add_u64 v[220:221], s[60:61], 0, v[134:135]
	s_addc_u32 s93, s61, 0
	s_add_i32 s91, s79, s68
	global_load_lds_dwordx4 v[220:221], off
	v_lshl_add_u64 v[222:223], s[92:93], 0, v[132:133]
	s_mov_b32 m0, s91
	v_lshl_add_u64 v[226:227], s[62:63], 0, v[130:131]
	global_load_lds_dwordx4 v[222:223], off
	v_lshl_add_u64 v[222:223], s[92:93], 0, v[134:135]
	s_add_i32 m0, s91, 0x2000
	s_nop 0
	global_load_lds_dwordx4 v[222:223], off
	v_lshl_add_u64 v[222:223], s[62:63], 0, v[128:129]
	s_mov_b32 m0, s69
	s_nop 0
	global_load_lds_dwordx4 v[222:223], off
	s_mov_b32 m0, s70
	s_nop 0
	global_load_lds_dwordx4 v[226:227], off
	s_waitcnt vmcnt(8)
	s_waitcnt lgkmcnt(0)
	s_barrier
; #define PG8_STAGE(bufoff, gbase, voff) do { _Pragma("unroll") for (int _i = 0; _i < 2; ++_i) \
;         __builtin_amdgcn_global_load_lds((const unsigned*)((const char*)(gbase) + (voff)[_i]), (LAS unsigned*)(lds + (bufoff) + ldsw + _i * 8192), 16, 0, 0); } while (0)
; #define PG8_LDA(dst, b, h) do { _Pragma("unroll") for (int m = 0; m < 4; ++m) _Pragma("unroll") for (int k = 0; k < 2; ++k) dst[m][k] = *(const LAS bf16x8*)(lds + PG8_SA(b, h) + aoff + m * 2048 + k * 1024); } while (0)
; #define PG8_LDB(dst, b, h) do { _Pragma("unroll") for (int n = 0; n < 2; ++n) _Pragma("unroll") for (int k = 0; k < 2; ++k) dst[n][k] = *(const LAS bf16x8*)(lds + PG8_SB(b, h) + boff + n * 2048 + k * 1024); } while (0)
; #define PG8_MMA(ai, bj, At, Bt) do { __builtin_amdgcn_s_setprio(1); _Pragma("unroll") for (int m = 0; m < 4; ++m) _Pragma("unroll") for (int n = 0; n < 2; ++n) _Pragma("unroll") for (int k = 0; k < 2; ++k) \
;         acc[ai][bj][m][n] = __builtin_amdgcn_mfma_f32_16x16x32_bf16(Bt[n][k], At[m][k], acc[ai][bj][m][n], 0, 0, 0); __builtin_amdgcn_s_setprio(0); } while (0)
; #define PG8_WAIT_V(n) asm volatile("s_waitcnt vmcnt(" #n ")" ::: "memory")
; #define PG8_WAIT_L(n) asm volatile("s_waitcnt lgkmcnt(" #n ")" ::: "memory")
; #define PG8_BAR __builtin_amdgcn_s_barrier()
; #define PG8_SCHED __builtin_amdgcn_sched_barrier(0)
; template <class Epi, bool ALIGN_EPI = true, bool SP2 = true>
; DI void gemm_phase(LAS unsigned char* lds, const Gemm g, const StaticOrder& S, const Epi& E) {
;     ...
;             PG8_WAIT_V(8); PG8_WAIT_L(0); PG8_BAR; PG8_MMA(1, 0, At, B0); PG8_MMA(1, 1, At, B1); PG8_BAR; PG8_SCHED;
;             PG8_LDB(B0, 1, 0); PG8_LDB(B1, 1, 1); PG8_SCHED; PG8_LDA(At, 1, 0); PG8_STAGE(PG8_SA(0, 1), a2 + hstepA, voffA);
;             PG8_WAIT_V(8); PG8_WAIT_L(0); PG8_BAR; PG8_MMA(0, 0, At, B0); PG8_MMA(0, 1, At, B1); PG8_BAR; PG8_SCHED;
	s_waitcnt lgkmcnt(0)
	v_mfma_f32_16x16x32_bf16 v[60:63], v[154:157], v[186:189], v[60:63]
	v_mfma_f32_16x16x32_bf16 v[56:59], v[162:165], v[186:189], v[56:59]
	v_mfma_f32_16x16x32_bf16 v[52:55], v[154:157], v[196:199], v[52:55]
	v_mfma_f32_16x16x32_bf16 v[48:51], v[162:165], v[196:199], v[48:51]
	v_mfma_f32_16x16x32_bf16 v[36:39], v[154:157], v[204:207], v[36:39]
	v_mfma_f32_16x16x32_bf16 v[32:35], v[162:165], v[204:207], v[32:35]
	v_mfma_f32_16x16x32_bf16 v[20:23], v[154:157], v[212:215], v[20:23]
	v_mfma_f32_16x16x32_bf16 v[16:19], v[162:165], v[212:215], v[16:19]
	v_mfma_f32_16x16x32_bf16 v[60:63], v[158:161], v[192:195], v[60:63]
	v_mfma_f32_16x16x32_bf16 v[56:59], v[166:169], v[192:195], v[56:59]
	v_mfma_f32_16x16x32_bf16 v[52:55], v[158:161], v[200:203], v[52:55]
	v_mfma_f32_16x16x32_bf16 v[48:51], v[166:169], v[200:203], v[48:51]
	v_mfma_f32_16x16x32_bf16 v[36:39], v[158:161], v[208:211], v[36:39]
	v_mfma_f32_16x16x32_bf16 v[32:35], v[166:169], v[208:211], v[32:35]
	v_mfma_f32_16x16x32_bf16 v[20:23], v[158:161], v[216:219], v[20:23]
	v_mfma_f32_16x16x32_bf16 v[16:19], v[166:169], v[216:219], v[16:19]
	v_mfma_f32_16x16x32_bf16 v[44:47], v[170:173], v[186:189], v[44:47]
	v_mfma_f32_16x16x32_bf16 v[40:43], v[178:181], v[186:189], v[40:43]
	v_mfma_f32_16x16x32_bf16 v[28:31], v[170:173], v[196:199], v[28:31]
	v_mfma_f32_16x16x32_bf16 v[24:27], v[178:181], v[196:199], v[24:27]
	v_mfma_f32_16x16x32_bf16 v[12:15], v[170:173], v[204:207], v[12:15]
	v_mfma_f32_16x16x32_bf16 v[8:11], v[178:181], v[204:207], v[8:11]
	v_mfma_f32_16x16x32_bf16 v[4:7], v[170:173], v[212:215], v[4:7]
	v_mfma_f32_16x16x32_bf16 v[0:3], v[178:181], v[212:215], v[0:3]
	v_mfma_f32_16x16x32_bf16 v[44:47], v[174:177], v[192:195], v[44:47]
	v_mfma_f32_16x16x32_bf16 v[40:43], v[182:185], v[192:195], v[40:43]
	v_mfma_f32_16x16x32_bf16 v[28:31], v[174:177], v[200:203], v[28:31]
	v_mfma_f32_16x16x32_bf16 v[24:27], v[182:185], v[200:203], v[24:27]
	v_mfma_f32_16x16x32_bf16 v[12:15], v[174:177], v[208:211], v[12:15]
	v_mfma_f32_16x16x32_bf16 v[8:11], v[182:185], v[208:211], v[8:11]
	v_mfma_f32_16x16x32_bf16 v[4:7], v[174:177], v[216:219], v[4:7]
	v_mfma_f32_16x16x32_bf16 v[0:3], v[182:185], v[216:219], v[0:3]
	s_barrier
	s_add_i32 s91, 0, 0x18000
	v_add_u32_e32 v149, s91, v147
	s_add_i32 s92, 0, 0x1c000
	ds_read_b128 v[154:157], v149
	ds_read_b128 v[158:161], v149 offset:1024
	ds_read_b128 v[162:165], v149 offset:2048
	ds_read_b128 v[166:169], v149 offset:3072
	v_add_u32_e32 v149, s92, v147
	ds_read_b128 v[170:173], v149
	ds_read_b128 v[174:177], v149 offset:1024
	ds_read_b128 v[178:181], v149 offset:2048
	ds_read_b128 v[182:185], v149 offset:3072
	s_add_u32 s62, s62, 0x480000
	s_addc_u32 s63, s63, 0
	s_mov_b32 m0, s71
	v_lshl_add_u64 v[228:229], s[62:63], 0, v[128:129]
	ds_read_b128 v[186:189], v148 offset:32768
	ds_read_b128 v[192:195], v148 offset:33792
	ds_read_b128 v[196:199], v148 offset:34816
	ds_read_b128 v[200:203], v148 offset:35840
	ds_read_b128 v[204:207], v148 offset:36864
	ds_read_b128 v[208:211], v148 offset:37888
	ds_read_b128 v[212:215], v148 offset:38912
	ds_read_b128 v[216:219], v148 offset:39936
	global_load_lds_dwordx4 v[228:229], off
	v_lshl_add_u64 v[228:229], s[62:63], 0, v[130:131]
	s_mov_b32 m0, s72
	s_nop 0
	global_load_lds_dwordx4 v[228:229], off
	s_waitcnt vmcnt(8)
	s_waitcnt lgkmcnt(0)
	s_barrier
	s_waitcnt lgkmcnt(0)
	v_mfma_f32_16x16x32_bf16 v[124:127], v[154:157], v[186:189], v[124:127]
	v_mfma_f32_16x16x32_bf16 v[120:123], v[162:165], v[186:189], v[120:123]
	v_mfma_f32_16x16x32_bf16 v[116:119], v[154:157], v[196:199], v[116:119]
	v_mfma_f32_16x16x32_bf16 v[112:115], v[162:165], v[196:199], v[112:115]
	v_mfma_f32_16x16x32_bf16 v[100:103], v[154:157], v[204:207], v[100:103]
	v_mfma_f32_16x16x32_bf16 v[96:99], v[162:165], v[204:207], v[96:99]
	v_mfma_f32_16x16x32_bf16 v[84:87], v[154:157], v[212:215], v[84:87]
	v_mfma_f32_16x16x32_bf16 v[80:83], v[162:165], v[212:215], v[80:83]
	v_mfma_f32_16x16x32_bf16 v[124:127], v[158:161], v[192:195], v[124:127]
	v_mfma_f32_16x16x32_bf16 v[120:123], v[166:169], v[192:195], v[120:123]
	v_mfma_f32_16x16x32_bf16 v[116:119], v[158:161], v[200:203], v[116:119]
	v_mfma_f32_16x16x32_bf16 v[112:115], v[166:169], v[200:203], v[112:115]
	v_mfma_f32_16x16x32_bf16 v[100:103], v[158:161], v[208:211], v[100:103]
	v_mfma_f32_16x16x32_bf16 v[96:99], v[166:169], v[208:211], v[96:99]
	v_mfma_f32_16x16x32_bf16 v[84:87], v[158:161], v[216:219], v[84:87]
	v_mfma_f32_16x16x32_bf16 v[80:83], v[166:169], v[216:219], v[80:83]
	v_mfma_f32_16x16x32_bf16 v[108:111], v[170:173], v[186:189], v[108:111]
	v_mfma_f32_16x16x32_bf16 v[104:107], v[178:181], v[186:189], v[104:107]
	v_mfma_f32_16x16x32_bf16 v[92:95], v[170:173], v[196:199], v[92:95]
	v_mfma_f32_16x16x32_bf16 v[88:91], v[178:181], v[196:199], v[88:91]
	v_mfma_f32_16x16x32_bf16 v[76:79], v[170:173], v[204:207], v[76:79]
	v_mfma_f32_16x16x32_bf16 v[72:75], v[178:181], v[204:207], v[72:75]
	v_mfma_f32_16x16x32_bf16 v[68:71], v[170:173], v[212:215], v[68:71]
	v_mfma_f32_16x16x32_bf16 v[64:67], v[178:181], v[212:215], v[64:67]
	v_mfma_f32_16x16x32_bf16 v[108:111], v[174:177], v[192:195], v[108:111]
	v_mfma_f32_16x16x32_bf16 v[104:107], v[182:185], v[192:195], v[104:107]
	v_mfma_f32_16x16x32_bf16 v[92:95], v[174:177], v[200:203], v[92:95]
	v_mfma_f32_16x16x32_bf16 v[88:91], v[182:185], v[200:203], v[88:91]
	v_mfma_f32_16x16x32_bf16 v[76:79], v[174:177], v[208:211], v[76:79]
	v_mfma_f32_16x16x32_bf16 v[72:75], v[182:185], v[208:211], v[72:75]
	v_mfma_f32_16x16x32_bf16 v[68:71], v[174:177], v[216:219], v[68:71]
	v_mfma_f32_16x16x32_bf16 v[64:67], v[182:185], v[216:219], v[64:67]
	s_barrier
; #define PG8_STAGE(bufoff, gbase, voff) do { _Pragma("unroll") for (int _i = 0; _i < 2; ++_i) \
;         __builtin_amdgcn_global_load_lds((const unsigned*)((const char*)(gbase) + (voff)[_i]), (LAS unsigned*)(lds + (bufoff) + ldsw + _i * 8192), 16, 0, 0); } while (0)
; #define PG8_LDA(dst, b, h) do { _Pragma("unroll") for (int m = 0; m < 4; ++m) _Pragma("unroll") for (int k = 0; k < 2; ++k) dst[m][k] = *(const LAS bf16x8*)(lds + PG8_SA(b, h) + aoff + m * 2048 + k * 1024); } while (0)
; #define PG8_MMA(ai, bj, At, Bt) do { __builtin_amdgcn_s_setprio(1); _Pragma("unroll") for (int m = 0; m < 4; ++m) _Pragma("unroll") for (int n = 0; n < 2; ++n) _Pragma("unroll") for (int k = 0; k < 2; ++k) \
;         acc[ai][bj][m][n] = __builtin_amdgcn_mfma_f32_16x16x32_bf16(Bt[n][k], At[m][k], acc[ai][bj][m][n], 0, 0, 0); __builtin_amdgcn_s_setprio(0); } while (0)
; #define PG8_WAIT_V(n) asm volatile("s_waitcnt vmcnt(" #n ")" ::: "memory")
; #define PG8_WAIT_L(n) asm volatile("s_waitcnt lgkmcnt(" #n ")" ::: "memory")
; #define PG8_BAR __builtin_amdgcn_s_barrier()
; #define PG8_SCHED __builtin_amdgcn_sched_barrier(0)
; template <class Epi, bool ALIGN_EPI = true, bool SP2 = true>
; DI void gemm_phase(LAS unsigned char* lds, const Gemm g, const StaticOrder& S, const Epi& E) {
;     ...
;             PG8_LDA(At, 1, 1); PG8_STAGE(PG8_SB(1, 0), b3, voffB); PG8_STAGE(PG8_SB(1, 1), b3 + hstepB, voffB); PG8_STAGE(PG8_SA(1, 0), a3, voffA);
;             PG8_WAIT_V(8); PG8_WAIT_L(0); PG8_BAR; PG8_MMA(1, 0, At, B0); PG8_MMA(1, 1, At, B1); PG8_BAR; PG8_SCHED;
;     ...
;         if constexpr (ALIGN_EPI) { if (wr == 0) PG8_BAR; }
	s_add_i32 s62, s91, s68
	v_lshl_add_u64 v[150:151], v[150:151], 0, s[20:21]
	s_mov_b32 m0, s62
	ds_read_b128 v[186:189], v148 offset:49152
	ds_read_b128 v[192:195], v148 offset:50176
	ds_read_b128 v[196:199], v148 offset:51200
	ds_read_b128 v[200:203], v148 offset:52224
	ds_read_b128 v[204:207], v148 offset:53248
	ds_read_b128 v[208:211], v148 offset:54272
	ds_read_b128 v[212:215], v148 offset:55296
	ds_read_b128 v[216:219], v148 offset:56320
	global_load_lds_dwordx4 v[150:151], off
	s_add_i32 m0, s62, 0x2000
	s_add_u32 s60, s60, 0x20080
	v_lshl_add_u64 v[150:151], v[220:221], 0, s[20:21]
	s_addc_u32 s61, s61, 0
	s_add_i32 s62, s92, s68
	global_load_lds_dwordx4 v[150:151], off
	v_lshl_add_u64 v[150:151], s[60:61], 0, v[132:133]
	s_mov_b32 m0, s62
	s_nop 0
	global_load_lds_dwordx4 v[150:151], off
	v_lshl_add_u64 v[150:151], s[60:61], 0, v[134:135]
	s_add_i32 m0, s62, 0x2000
	s_nop 0
	global_load_lds_dwordx4 v[150:151], off
	v_lshl_add_u64 v[150:151], v[222:223], 0, s[20:21]
	s_mov_b32 m0, s74
	s_nop 0
	global_load_lds_dwordx4 v[150:151], off
	v_lshl_add_u64 v[150:151], v[226:227], 0, s[20:21]
	s_mov_b32 m0, s75
	s_nop 0
	global_load_lds_dwordx4 v[150:151], off
	s_waitcnt vmcnt(8)
	s_waitcnt lgkmcnt(0)
	s_barrier
	s_waitcnt lgkmcnt(0)
	v_mfma_f32_16x16x32_bf16 v[60:63], v[154:157], v[186:189], v[60:63]
	v_mfma_f32_16x16x32_bf16 v[56:59], v[162:165], v[186:189], v[56:59]
	v_mfma_f32_16x16x32_bf16 v[52:55], v[154:157], v[196:199], v[52:55]
	v_mfma_f32_16x16x32_bf16 v[48:51], v[162:165], v[196:199], v[48:51]
	v_mfma_f32_16x16x32_bf16 v[36:39], v[154:157], v[204:207], v[36:39]
	v_mfma_f32_16x16x32_bf16 v[32:35], v[162:165], v[204:207], v[32:35]
	v_mfma_f32_16x16x32_bf16 v[20:23], v[154:157], v[212:215], v[20:23]
	v_mfma_f32_16x16x32_bf16 v[16:19], v[162:165], v[212:215], v[16:19]
	v_mfma_f32_16x16x32_bf16 v[60:63], v[158:161], v[192:195], v[60:63]
	v_mfma_f32_16x16x32_bf16 v[56:59], v[166:169], v[192:195], v[56:59]
	v_mfma_f32_16x16x32_bf16 v[52:55], v[158:161], v[200:203], v[52:55]
	v_mfma_f32_16x16x32_bf16 v[48:51], v[166:169], v[200:203], v[48:51]
	v_mfma_f32_16x16x32_bf16 v[36:39], v[158:161], v[208:211], v[36:39]
	v_mfma_f32_16x16x32_bf16 v[32:35], v[166:169], v[208:211], v[32:35]
	v_mfma_f32_16x16x32_bf16 v[20:23], v[158:161], v[216:219], v[20:23]
	v_mfma_f32_16x16x32_bf16 v[16:19], v[166:169], v[216:219], v[16:19]
	v_mfma_f32_16x16x32_bf16 v[44:47], v[170:173], v[186:189], v[44:47]
	v_mfma_f32_16x16x32_bf16 v[40:43], v[178:181], v[186:189], v[40:43]
	v_mfma_f32_16x16x32_bf16 v[28:31], v[170:173], v[196:199], v[28:31]
	v_mfma_f32_16x16x32_bf16 v[24:27], v[178:181], v[196:199], v[24:27]
	v_mfma_f32_16x16x32_bf16 v[12:15], v[170:173], v[204:207], v[12:15]
	v_mfma_f32_16x16x32_bf16 v[8:11], v[178:181], v[204:207], v[8:11]
	v_mfma_f32_16x16x32_bf16 v[4:7], v[170:173], v[212:215], v[4:7]
	v_mfma_f32_16x16x32_bf16 v[0:3], v[178:181], v[212:215], v[0:3]
	v_mfma_f32_16x16x32_bf16 v[44:47], v[174:177], v[192:195], v[44:47]
	v_mfma_f32_16x16x32_bf16 v[40:43], v[182:185], v[192:195], v[40:43]
	v_mfma_f32_16x16x32_bf16 v[28:31], v[174:177], v[200:203], v[28:31]
	v_mfma_f32_16x16x32_bf16 v[24:27], v[182:185], v[200:203], v[24:27]
	v_mfma_f32_16x16x32_bf16 v[12:15], v[174:177], v[208:211], v[12:15]
	v_mfma_f32_16x16x32_bf16 v[8:11], v[182:185], v[208:211], v[8:11]
	v_mfma_f32_16x16x32_bf16 v[4:7], v[174:177], v[216:219], v[4:7]
	v_mfma_f32_16x16x32_bf16 v[0:3], v[182:185], v[216:219], v[0:3]
	s_barrier
	s_add_i32 s90, s90, 2
	s_add_u32 s0, s0, 0x100
	s_addc_u32 s1, s1, 0
	s_add_u32 s88, s88, 0x100
	s_addc_u32 s89, s89, 0
	s_cmp_gt_u32 s90, 5
	s_cbranch_scc0 .LBB0_360
	s_and_b64 vcc, exec, s[22:23]
	s_cbranch_vccz .LBB0_363
	s_barrier

; #define PG8_STAGE(bufoff, gbase, voff) do { _Pragma("unroll") for (int _i = 0; _i < 2; ++_i) \
;         __builtin_amdgcn_global_load_lds((const unsigned*)((const char*)(gbase) + (voff)[_i]), (LAS unsigned*)(lds + (bufoff) + ldsw + _i * 8192), 16, 0, 0); } while (0)
; #define PG8_LDA(dst, b, h) do { _Pragma("unroll") for (int m = 0; m < 4; ++m) _Pragma("unroll") for (int k = 0; k < 2; ++k) dst[m][k] = *(const LAS bf16x8*)(lds + PG8_SA(b, h) + aoff + m * 2048 + k * 1024); } while (0)
; #define PG8_LDB(dst, b, h) do { _Pragma("unroll") for (int n = 0; n < 2; ++n) _Pragma("unroll") for (int k = 0; k < 2; ++k) dst[n][k] = *(const LAS bf16x8*)(lds + PG8_SB(b, h) + boff + n * 2048 + k * 1024); } while (0)
; #define PG8_MMA(ai, bj, At, Bt) do { __builtin_amdgcn_s_setprio(1); _Pragma("unroll") for (int m = 0; m < 4; ++m) _Pragma("unroll") for (int n = 0; n < 2; ++n) _Pragma("unroll") for (int k = 0; k < 2; ++k) \
;         acc[ai][bj][m][n] = __builtin_amdgcn_mfma_f32_16x16x32_bf16(Bt[n][k], At[m][k], acc[ai][bj][m][n], 0, 0, 0); __builtin_amdgcn_s_setprio(0); } while (0)
; #define PG8_BAR __builtin_amdgcn_s_barrier()
; template <class Epi, bool ALIGN_EPI = true, bool SP2 = true>
; DI void gemm_phase(LAS unsigned char* lds, const Gemm g, const StaticOrder& S, const Epi& E) {
;     ...
;             const bool last = (t == nt - 2);
;             const char* a1 = cA + (size_t)(t + 1) * kstep;
;             const char* a2 = last ? nA : cA + (size_t)(t + 2) * kstep; const char* b2 = last ? nB : cB + (size_t)(t + 2) * kstep;
;             const char* a3 = a2 + kstep; const char* b3 = b2 + kstep;
;             if (Epi::MID) { if (t == (nt >> 1)) {
;                 if constexpr (ALIGN_EPI) { if (wr == 0) PG8_BAR; }
;                 E.mid(acc, cur, wr, wc, fr, fq);
;                 if constexpr (ALIGN_EPI) { if (wr == 1) PG8_BAR; } } }
;             if constexpr (SP2) {
;             PG8_LDB(B0, 0, 0); PG8_LDB(B1, 0, 1); PG8_SCHED; PG8_LDA(At, 0, 0); PG8_STAGE(PG8_SA(1, 1), a1 + hstepA, voffA);
;             PG8_WAIT_V(8); PG8_WAIT_L(0); PG8_BAR; PG8_MMA(0, 0, At, B0); PG8_MMA(0, 1, At, B1); PG8_BAR; PG8_SCHED;
;             PG8_LDA(At, 0, 1); PG8_STAGE(PG8_SB(0, 0), b2, voffB); PG8_STAGE(PG8_SB(0, 1), b2 + hstepB, voffB); PG8_STAGE(PG8_SA(0, 0), a2, voffA);
;             PG8_WAIT_V(8); PG8_WAIT_L(0); PG8_BAR; PG8_MMA(1, 0, At, B0); PG8_MMA(1, 1, At, B1); PG8_BAR; PG8_SCHED;
.LBB0_755:
	v_add_u32_e32 v1, s67, v227
	ds_read_b128 v[132:135], v1
	ds_read_b128 v[136:139], v1 offset:1024
	ds_read_b128 v[140:143], v1 offset:2048
	ds_read_b128 v[144:147], v1 offset:3072
	v_add_u32_e32 v1, s68, v227
	s_add_u32 s8, s26, s30
	ds_read_b128 v[148:151], v1
	ds_read_b128 v[152:155], v1 offset:1024
	ds_read_b128 v[156:159], v1 offset:2048
	ds_read_b128 v[160:163], v1 offset:3072
	s_addc_u32 s9, s27, s31
	s_add_u32 s8, s8, 0x100
	s_addc_u32 s9, s9, 0
	s_add_u32 s34, s73, s30
	s_addc_u32 s35, s74, s31
	s_cmpk_eq_i32 s30, 0x1f00
	s_cselect_b32 s37, s21, s9
	s_cselect_b32 s36, s69, s8
	s_cselect_b32 s35, s70, s35
	s_cselect_b32 s34, s71, s34
	v_lshl_add_u64 v[2:3], v[188:189], 0, s[30:31]
	s_add_i32 m0, s43, 0xc000
	ds_read_b128 v[164:167], v229
	ds_read_b128 v[168:171], v229 offset:1024
	ds_read_b128 v[172:175], v229 offset:2048
	ds_read_b128 v[176:179], v229 offset:3072
	ds_read_b128 v[180:183], v229 offset:4096
	ds_read_b128 v[184:187], v229 offset:5120
	ds_read_b128 v[212:215], v229 offset:6144
	ds_read_b128 v[216:219], v229 offset:7168
	global_load_lds_dwordx4 v[2:3], off
	v_lshl_add_u64 v[2:3], v[190:191], 0, s[30:31]
	s_add_i32 m0, s43, 0xe000
	s_nop 0
	global_load_lds_dwordx4 v[2:3], off
	s_waitcnt vmcnt(8)
	s_waitcnt lgkmcnt(0)
	s_barrier
	s_waitcnt lgkmcnt(0)
	v_mfma_f32_16x16x32_bf16 v[128:131], v[132:135], v[164:167], v[128:131]
	v_mfma_f32_16x16x32_bf16 v[124:127], v[140:143], v[164:167], v[124:127]
	v_mfma_f32_16x16x32_bf16 v[112:115], v[132:135], v[172:175], v[112:115]
	v_mfma_f32_16x16x32_bf16 v[108:111], v[140:143], v[172:175], v[108:111]
	v_mfma_f32_16x16x32_bf16 v[96:99], v[132:135], v[180:183], v[96:99]
	v_mfma_f32_16x16x32_bf16 v[92:95], v[140:143], v[180:183], v[92:95]
	v_mfma_f32_16x16x32_bf16 v[80:83], v[132:135], v[212:215], v[80:83]
	v_mfma_f32_16x16x32_bf16 v[76:79], v[140:143], v[212:215], v[76:79]
	v_mfma_f32_16x16x32_bf16 v[128:131], v[136:139], v[168:171], v[128:131]
	v_mfma_f32_16x16x32_bf16 v[124:127], v[144:147], v[168:171], v[124:127]
	v_mfma_f32_16x16x32_bf16 v[112:115], v[136:139], v[176:179], v[112:115]
	v_mfma_f32_16x16x32_bf16 v[108:111], v[144:147], v[176:179], v[108:111]
	v_mfma_f32_16x16x32_bf16 v[96:99], v[136:139], v[184:187], v[96:99]
	v_mfma_f32_16x16x32_bf16 v[92:95], v[144:147], v[184:187], v[92:95]
	v_mfma_f32_16x16x32_bf16 v[80:83], v[136:139], v[216:219], v[80:83]
	v_mfma_f32_16x16x32_bf16 v[76:79], v[144:147], v[216:219], v[76:79]
	v_mfma_f32_16x16x32_bf16 v[120:123], v[148:151], v[164:167], v[120:123]
	v_mfma_f32_16x16x32_bf16 v[116:119], v[156:159], v[164:167], v[116:119]
	v_mfma_f32_16x16x32_bf16 v[104:107], v[148:151], v[172:175], v[104:107]
	v_mfma_f32_16x16x32_bf16 v[100:103], v[156:159], v[172:175], v[100:103]
	v_mfma_f32_16x16x32_bf16 v[88:91], v[148:151], v[180:183], v[88:91]
	v_mfma_f32_16x16x32_bf16 v[84:87], v[156:159], v[180:183], v[84:87]
	v_mfma_f32_16x16x32_bf16 v[72:75], v[148:151], v[212:215], v[72:75]
	v_mfma_f32_16x16x32_bf16 v[68:71], v[156:159], v[212:215], v[68:71]
	v_mfma_f32_16x16x32_bf16 v[120:123], v[152:155], v[168:171], v[120:123]
	v_mfma_f32_16x16x32_bf16 v[116:119], v[160:163], v[168:171], v[116:119]
	v_mfma_f32_16x16x32_bf16 v[104:107], v[152:155], v[176:179], v[104:107]
	v_mfma_f32_16x16x32_bf16 v[100:103], v[160:163], v[176:179], v[100:103]
	v_mfma_f32_16x16x32_bf16 v[88:91], v[152:155], v[184:187], v[88:91]
	v_mfma_f32_16x16x32_bf16 v[84:87], v[160:163], v[184:187], v[84:87]
	v_mfma_f32_16x16x32_bf16 v[72:75], v[152:155], v[216:219], v[72:75]
	v_mfma_f32_16x16x32_bf16 v[68:71], v[160:163], v[216:219], v[68:71]
	s_barrier
	s_add_i32 s8, s67, s42
	v_lshl_add_u64 v[220:221], s[34:35], 0, v[194:195]
	s_mov_b32 m0, s8
	ds_read_b128 v[164:167], v229 offset:16384
	ds_read_b128 v[168:171], v229 offset:17408
	ds_read_b128 v[172:175], v229 offset:18432
	ds_read_b128 v[176:179], v229 offset:19456
	ds_read_b128 v[180:183], v229 offset:20480
	ds_read_b128 v[184:187], v229 offset:21504
	ds_read_b128 v[212:215], v229 offset:22528
	ds_read_b128 v[216:219], v229 offset:23552
	global_load_lds_dwordx4 v[220:221], off
	s_add_i32 m0, s8, 0x2000
	s_add_u32 s76, s34, 0x100000
	v_lshl_add_u64 v[222:223], s[34:35], 0, v[198:199]
	s_addc_u32 s77, s35, 0
	s_add_i32 s8, s68, s42
	global_load_lds_dwordx4 v[222:223], off
	v_lshl_add_u64 v[2:3], s[76:77], 0, v[194:195]
	s_mov_b32 m0, s8
	v_lshl_add_u64 v[232:233], s[36:37], 0, v[192:193]
	global_load_lds_dwordx4 v[2:3], off
	v_lshl_add_u64 v[2:3], s[76:77], 0, v[198:199]
	s_add_i32 m0, s8, 0x2000
	v_lshl_add_u64 v[234:235], s[36:37], 0, v[196:197]
	global_load_lds_dwordx4 v[2:3], off
	s_mov_b32 m0, s43
	s_nop 0
	global_load_lds_dwordx4 v[232:233], off
	s_mov_b32 m0, s44
	s_nop 0
	global_load_lds_dwordx4 v[234:235], off
	s_waitcnt vmcnt(8)
	s_waitcnt lgkmcnt(0)
	s_barrier
; #define PG8_STAGE(bufoff, gbase, voff) do { _Pragma("unroll") for (int _i = 0; _i < 2; ++_i) \
;         __builtin_amdgcn_global_load_lds((const unsigned*)((const char*)(gbase) + (voff)[_i]), (LAS unsigned*)(lds + (bufoff) + ldsw + _i * 8192), 16, 0, 0); } while (0)
; #define PG8_LDA(dst, b, h) do { _Pragma("unroll") for (int m = 0; m < 4; ++m) _Pragma("unroll") for (int k = 0; k < 2; ++k) dst[m][k] = *(const LAS bf16x8*)(lds + PG8_SA(b, h) + aoff + m * 2048 + k * 1024); } while (0)
; #define PG8_LDB(dst, b, h) do { _Pragma("unroll") for (int n = 0; n < 2; ++n) _Pragma("unroll") for (int k = 0; k < 2; ++k) dst[n][k] = *(const LAS bf16x8*)(lds + PG8_SB(b, h) + boff + n * 2048 + k * 1024); } while (0)
; #define PG8_MMA(ai, bj, At, Bt) do { __builtin_amdgcn_s_setprio(1); _Pragma("unroll") for (int m = 0; m < 4; ++m) _Pragma("unroll") for (int n = 0; n < 2; ++n) _Pragma("unroll") for (int k = 0; k < 2; ++k) \
;         acc[ai][bj][m][n] = __builtin_amdgcn_mfma_f32_16x16x32_bf16(Bt[n][k], At[m][k], acc[ai][bj][m][n], 0, 0, 0); __builtin_amdgcn_s_setprio(0); } while (0)
; #define PG8_WAIT_V(n) asm volatile("s_waitcnt vmcnt(" #n ")" ::: "memory")
; #define PG8_WAIT_L(n) asm volatile("s_waitcnt lgkmcnt(" #n ")" ::: "memory")
; #define PG8_BAR __builtin_amdgcn_s_barrier()
; #define PG8_SCHED __builtin_amdgcn_sched_barrier(0)
; template <class Epi, bool ALIGN_EPI = true, bool SP2 = true>
; DI void gemm_phase(LAS unsigned char* lds, const Gemm g, const StaticOrder& S, const Epi& E) {
;     ...
;             PG8_WAIT_V(8); PG8_WAIT_L(0); PG8_BAR; PG8_MMA(1, 0, At, B0); PG8_MMA(1, 1, At, B1); PG8_BAR; PG8_SCHED;
;             PG8_LDB(B0, 1, 0); PG8_LDB(B1, 1, 1); PG8_SCHED; PG8_LDA(At, 1, 0); PG8_STAGE(PG8_SA(0, 1), a2 + hstepA, voffA);
;             PG8_WAIT_V(8); PG8_WAIT_L(0); PG8_BAR; PG8_MMA(0, 0, At, B0); PG8_MMA(0, 1, At, B1); PG8_BAR; PG8_SCHED;
	s_waitcnt lgkmcnt(0)
	v_mfma_f32_16x16x32_bf16 v[64:67], v[132:135], v[164:167], v[64:67]
	v_mfma_f32_16x16x32_bf16 v[60:63], v[140:143], v[164:167], v[60:63]
	v_mfma_f32_16x16x32_bf16 v[48:51], v[132:135], v[172:175], v[48:51]
	v_mfma_f32_16x16x32_bf16 v[44:47], v[140:143], v[172:175], v[44:47]
	v_mfma_f32_16x16x32_bf16 v[32:35], v[132:135], v[180:183], v[32:35]
	v_mfma_f32_16x16x32_bf16 v[28:31], v[140:143], v[180:183], v[28:31]
	v_mfma_f32_16x16x32_bf16 v[16:19], v[132:135], v[212:215], v[16:19]
	v_mfma_f32_16x16x32_bf16 v[12:15], v[140:143], v[212:215], v[12:15]
	v_mfma_f32_16x16x32_bf16 v[64:67], v[136:139], v[168:171], v[64:67]
	v_mfma_f32_16x16x32_bf16 v[60:63], v[144:147], v[168:171], v[60:63]
	v_mfma_f32_16x16x32_bf16 v[48:51], v[136:139], v[176:179], v[48:51]
	v_mfma_f32_16x16x32_bf16 v[44:47], v[144:147], v[176:179], v[44:47]
	v_mfma_f32_16x16x32_bf16 v[32:35], v[136:139], v[184:187], v[32:35]
	v_mfma_f32_16x16x32_bf16 v[28:31], v[144:147], v[184:187], v[28:31]
	v_mfma_f32_16x16x32_bf16 v[16:19], v[136:139], v[216:219], v[16:19]
	v_mfma_f32_16x16x32_bf16 v[12:15], v[144:147], v[216:219], v[12:15]
	v_mfma_f32_16x16x32_bf16 v[56:59], v[148:151], v[164:167], v[56:59]
	v_mfma_f32_16x16x32_bf16 v[52:55], v[156:159], v[164:167], v[52:55]
	v_mfma_f32_16x16x32_bf16 v[40:43], v[148:151], v[172:175], v[40:43]
	v_mfma_f32_16x16x32_bf16 v[36:39], v[156:159], v[172:175], v[36:39]
	v_mfma_f32_16x16x32_bf16 v[24:27], v[148:151], v[180:183], v[24:27]
	v_mfma_f32_16x16x32_bf16 v[20:23], v[156:159], v[180:183], v[20:23]
	v_mfma_f32_16x16x32_bf16 v[8:11], v[148:151], v[212:215], v[8:11]
	v_mfma_f32_16x16x32_bf16 v[2:5], v[156:159], v[212:215], v[4:7]
	v_mfma_f32_16x16x32_bf16 v[56:59], v[152:155], v[168:171], v[56:59]
	v_mfma_f32_16x16x32_bf16 v[52:55], v[160:163], v[168:171], v[52:55]
	v_mfma_f32_16x16x32_bf16 v[40:43], v[152:155], v[176:179], v[40:43]
	v_mfma_f32_16x16x32_bf16 v[36:39], v[160:163], v[176:179], v[36:39]
	v_mfma_f32_16x16x32_bf16 v[24:27], v[152:155], v[184:187], v[24:27]
	v_mfma_f32_16x16x32_bf16 v[20:23], v[160:163], v[184:187], v[20:23]
	v_mfma_f32_16x16x32_bf16 v[8:11], v[152:155], v[216:219], v[8:11]
	v_mfma_f32_16x16x32_bf16 v[2:5], v[160:163], v[216:219], v[2:5]
	s_barrier
	s_add_i32 s8, 0, 0x18000
	v_add_u32_e32 v1, s8, v227
	s_add_i32 s9, 0, 0x1c000
	ds_read_b128 v[132:135], v1
	ds_read_b128 v[136:139], v1 offset:1024
	ds_read_b128 v[140:143], v1 offset:2048
	ds_read_b128 v[144:147], v1 offset:3072
	v_add_u32_e32 v1, s9, v227
	ds_read_b128 v[148:151], v1
	ds_read_b128 v[152:155], v1 offset:1024
	ds_read_b128 v[156:159], v1 offset:2048
	ds_read_b128 v[160:163], v1 offset:3072
	s_add_u32 s36, s36, 0x100000
	s_addc_u32 s37, s37, 0
	s_mov_b32 m0, s45
	v_lshl_add_u64 v[6:7], s[36:37], 0, v[192:193]
	ds_read_b128 v[164:167], v229 offset:32768
	ds_read_b128 v[168:171], v229 offset:33792
	ds_read_b128 v[172:175], v229 offset:34816
	ds_read_b128 v[176:179], v229 offset:35840
	ds_read_b128 v[180:183], v229 offset:36864
	ds_read_b128 v[184:187], v229 offset:37888
	ds_read_b128 v[212:215], v229 offset:38912
	ds_read_b128 v[216:219], v229 offset:39936
	global_load_lds_dwordx4 v[6:7], off
	v_lshl_add_u64 v[6:7], s[36:37], 0, v[196:197]
	s_mov_b32 m0, s46
	s_nop 0
	global_load_lds_dwordx4 v[6:7], off
	s_waitcnt vmcnt(8)
	s_waitcnt lgkmcnt(0)
	s_barrier
	s_waitcnt lgkmcnt(0)
	v_mfma_f32_16x16x32_bf16 v[128:131], v[132:135], v[164:167], v[128:131]
	v_mfma_f32_16x16x32_bf16 v[124:127], v[140:143], v[164:167], v[124:127]
	v_mfma_f32_16x16x32_bf16 v[112:115], v[132:135], v[172:175], v[112:115]
	v_mfma_f32_16x16x32_bf16 v[108:111], v[140:143], v[172:175], v[108:111]
	v_mfma_f32_16x16x32_bf16 v[96:99], v[132:135], v[180:183], v[96:99]
	v_mfma_f32_16x16x32_bf16 v[92:95], v[140:143], v[180:183], v[92:95]
	v_mfma_f32_16x16x32_bf16 v[80:83], v[132:135], v[212:215], v[80:83]
	v_mfma_f32_16x16x32_bf16 v[76:79], v[140:143], v[212:215], v[76:79]
	v_mfma_f32_16x16x32_bf16 v[128:131], v[136:139], v[168:171], v[128:131]
	v_mfma_f32_16x16x32_bf16 v[124:127], v[144:147], v[168:171], v[124:127]
	v_mfma_f32_16x16x32_bf16 v[112:115], v[136:139], v[176:179], v[112:115]
	v_mfma_f32_16x16x32_bf16 v[108:111], v[144:147], v[176:179], v[108:111]
	v_mfma_f32_16x16x32_bf16 v[96:99], v[136:139], v[184:187], v[96:99]
	v_mfma_f32_16x16x32_bf16 v[92:95], v[144:147], v[184:187], v[92:95]
	v_mfma_f32_16x16x32_bf16 v[80:83], v[136:139], v[216:219], v[80:83]
	v_mfma_f32_16x16x32_bf16 v[76:79], v[144:147], v[216:219], v[76:79]
	v_mfma_f32_16x16x32_bf16 v[120:123], v[148:151], v[164:167], v[120:123]
	v_mfma_f32_16x16x32_bf16 v[116:119], v[156:159], v[164:167], v[116:119]
	v_mfma_f32_16x16x32_bf16 v[104:107], v[148:151], v[172:175], v[104:107]
	v_mfma_f32_16x16x32_bf16 v[100:103], v[156:159], v[172:175], v[100:103]
	v_mfma_f32_16x16x32_bf16 v[88:91], v[148:151], v[180:183], v[88:91]
	v_mfma_f32_16x16x32_bf16 v[84:87], v[156:159], v[180:183], v[84:87]
	v_mfma_f32_16x16x32_bf16 v[72:75], v[148:151], v[212:215], v[72:75]
	v_mfma_f32_16x16x32_bf16 v[68:71], v[156:159], v[212:215], v[68:71]
	v_mfma_f32_16x16x32_bf16 v[120:123], v[152:155], v[168:171], v[120:123]
	v_mfma_f32_16x16x32_bf16 v[116:119], v[160:163], v[168:171], v[116:119]
	v_mfma_f32_16x16x32_bf16 v[104:107], v[152:155], v[176:179], v[104:107]
	v_mfma_f32_16x16x32_bf16 v[100:103], v[160:163], v[176:179], v[100:103]
	v_mfma_f32_16x16x32_bf16 v[88:91], v[152:155], v[184:187], v[88:91]
	v_mfma_f32_16x16x32_bf16 v[84:87], v[160:163], v[184:187], v[84:87]
	v_mfma_f32_16x16x32_bf16 v[72:75], v[152:155], v[216:219], v[72:75]
	v_mfma_f32_16x16x32_bf16 v[68:71], v[160:163], v[216:219], v[68:71]
	s_barrier
; #define PG8_STAGE(bufoff, gbase, voff) do { _Pragma("unroll") for (int _i = 0; _i < 2; ++_i) \
;         __builtin_amdgcn_global_load_lds((const unsigned*)((const char*)(gbase) + (voff)[_i]), (LAS unsigned*)(lds + (bufoff) + ldsw + _i * 8192), 16, 0, 0); } while (0)
; #define PG8_LDA(dst, b, h) do { _Pragma("unroll") for (int m = 0; m < 4; ++m) _Pragma("unroll") for (int k = 0; k < 2; ++k) dst[m][k] = *(const LAS bf16x8*)(lds + PG8_SA(b, h) + aoff + m * 2048 + k * 1024); } while (0)
; #define PG8_MMA(ai, bj, At, Bt) do { __builtin_amdgcn_s_setprio(1); _Pragma("unroll") for (int m = 0; m < 4; ++m) _Pragma("unroll") for (int n = 0; n < 2; ++n) _Pragma("unroll") for (int k = 0; k < 2; ++k) \
;         acc[ai][bj][m][n] = __builtin_amdgcn_mfma_f32_16x16x32_bf16(Bt[n][k], At[m][k], acc[ai][bj][m][n], 0, 0, 0); __builtin_amdgcn_s_setprio(0); } while (0)
; #define PG8_WAIT_V(n) asm volatile("s_waitcnt vmcnt(" #n ")" ::: "memory")
; #define PG8_WAIT_L(n) asm volatile("s_waitcnt lgkmcnt(" #n ")" ::: "memory")
; #define PG8_BAR __builtin_amdgcn_s_barrier()
; #define PG8_SCHED __builtin_amdgcn_sched_barrier(0)
; template <class Epi, bool ALIGN_EPI = true, bool SP2 = true>
; DI void gemm_phase(LAS unsigned char* lds, const Gemm g, const StaticOrder& S, const Epi& E) {
;     ...
;         for (int t = 0; t < nt; t += 2) {
;     ...
;             PG8_LDA(At, 1, 1); PG8_STAGE(PG8_SB(1, 0), b3, voffB); PG8_STAGE(PG8_SB(1, 1), b3 + hstepB, voffB); PG8_STAGE(PG8_SA(1, 0), a3, voffA);
;             PG8_WAIT_V(8); PG8_WAIT_L(0); PG8_BAR; PG8_MMA(1, 0, At, B0); PG8_MMA(1, 1, At, B1); PG8_BAR; PG8_SCHED;
	s_add_i32 s8, s8, s42
	v_lshl_add_u64 v[6:7], v[220:221], 0, s[10:11]
	s_mov_b32 m0, s8
	ds_read_b128 v[164:167], v229 offset:49152
	ds_read_b128 v[168:171], v229 offset:50176
	ds_read_b128 v[172:175], v229 offset:51200
	ds_read_b128 v[176:179], v229 offset:52224
	ds_read_b128 v[180:183], v229 offset:53248
	ds_read_b128 v[184:187], v229 offset:54272
	ds_read_b128 v[212:215], v229 offset:55296
	ds_read_b128 v[216:219], v229 offset:56320
	global_load_lds_dwordx4 v[6:7], off
	s_add_i32 m0, s8, 0x2000
	s_add_u32 s34, s34, 0x100080
	v_lshl_add_u64 v[6:7], v[222:223], 0, s[10:11]
	s_addc_u32 s35, s35, 0
	s_add_i32 s8, s9, s42
	global_load_lds_dwordx4 v[6:7], off
	v_lshl_add_u64 v[6:7], s[34:35], 0, v[194:195]
	s_mov_b32 m0, s8
	s_nop 0
	global_load_lds_dwordx4 v[6:7], off
	v_lshl_add_u64 v[6:7], s[34:35], 0, v[198:199]
	s_add_i32 m0, s8, 0x2000
	s_nop 0
	global_load_lds_dwordx4 v[6:7], off
	v_lshl_add_u64 v[6:7], v[232:233], 0, s[10:11]
	s_mov_b32 m0, s51
	s_nop 0
	global_load_lds_dwordx4 v[6:7], off
	v_lshl_add_u64 v[6:7], v[234:235], 0, s[10:11]
	s_mov_b32 m0, s60
	s_nop 0
	global_load_lds_dwordx4 v[6:7], off
	s_waitcnt vmcnt(8)
	s_waitcnt lgkmcnt(0)
	s_barrier
	s_waitcnt lgkmcnt(0)
	v_mfma_f32_16x16x32_bf16 v[64:67], v[132:135], v[164:167], v[64:67]
	v_mfma_f32_16x16x32_bf16 v[60:63], v[140:143], v[164:167], v[60:63]
	v_mfma_f32_16x16x32_bf16 v[48:51], v[132:135], v[172:175], v[48:51]
	v_mfma_f32_16x16x32_bf16 v[44:47], v[140:143], v[172:175], v[44:47]
	v_mfma_f32_16x16x32_bf16 v[32:35], v[132:135], v[180:183], v[32:35]
	v_mfma_f32_16x16x32_bf16 v[28:31], v[140:143], v[180:183], v[28:31]
	v_mfma_f32_16x16x32_bf16 v[16:19], v[132:135], v[212:215], v[16:19]
	v_mfma_f32_16x16x32_bf16 v[12:15], v[140:143], v[212:215], v[12:15]
	v_mfma_f32_16x16x32_bf16 v[64:67], v[136:139], v[168:171], v[64:67]
	v_mfma_f32_16x16x32_bf16 v[60:63], v[144:147], v[168:171], v[60:63]
	v_mfma_f32_16x16x32_bf16 v[48:51], v[136:139], v[176:179], v[48:51]
	v_mfma_f32_16x16x32_bf16 v[44:47], v[144:147], v[176:179], v[44:47]
	v_mfma_f32_16x16x32_bf16 v[32:35], v[136:139], v[184:187], v[32:35]
	v_mfma_f32_16x16x32_bf16 v[28:31], v[144:147], v[184:187], v[28:31]
	v_mfma_f32_16x16x32_bf16 v[16:19], v[136:139], v[216:219], v[16:19]
	v_mfma_f32_16x16x32_bf16 v[12:15], v[144:147], v[216:219], v[12:15]
	v_mfma_f32_16x16x32_bf16 v[56:59], v[148:151], v[164:167], v[56:59]
	v_mfma_f32_16x16x32_bf16 v[52:55], v[156:159], v[164:167], v[52:55]
	v_mfma_f32_16x16x32_bf16 v[40:43], v[148:151], v[172:175], v[40:43]
	v_mfma_f32_16x16x32_bf16 v[36:39], v[156:159], v[172:175], v[36:39]
	v_mfma_f32_16x16x32_bf16 v[24:27], v[148:151], v[180:183], v[24:27]
	v_mfma_f32_16x16x32_bf16 v[20:23], v[156:159], v[180:183], v[20:23]
	v_mfma_f32_16x16x32_bf16 v[6:9], v[148:151], v[212:215], v[8:11]
	v_mfma_f32_16x16x32_bf16 v[2:5], v[156:159], v[212:215], v[2:5]
	v_mfma_f32_16x16x32_bf16 v[56:59], v[152:155], v[168:171], v[56:59]
	v_mfma_f32_16x16x32_bf16 v[52:55], v[160:163], v[168:171], v[52:55]
	v_mfma_f32_16x16x32_bf16 v[40:43], v[152:155], v[176:179], v[40:43]
	v_mfma_f32_16x16x32_bf16 v[36:39], v[160:163], v[176:179], v[36:39]
	v_mfma_f32_16x16x32_bf16 v[24:27], v[152:155], v[184:187], v[24:27]
	v_mfma_f32_16x16x32_bf16 v[20:23], v[160:163], v[184:187], v[20:23]
	v_mfma_f32_16x16x32_bf16 v[8:11], v[152:155], v[216:219], v[6:9]
	v_mfma_f32_16x16x32_bf16 v[4:7], v[160:163], v[216:219], v[2:5]
	s_barrier
	s_add_i32 s75, s75, 2
	s_add_u32 s30, s30, 0x100
	s_addc_u32 s31, s31, 0
	s_cmp_gt_u32 s75, 61
	s_cbranch_scc1 .LBB0_761

; #define PG8_STAGE(bufoff, gbase, voff) do { _Pragma("unroll") for (int _i = 0; _i < 2; ++_i) \
;         __builtin_amdgcn_global_load_lds((const unsigned*)((const char*)(gbase) + (voff)[_i]), (LAS unsigned*)(lds + (bufoff) + ldsw + _i * 8192), 16, 0, 0); } while (0)
; #define PG8_LDA(dst, b, h) do { _Pragma("unroll") for (int m = 0; m < 4; ++m) _Pragma("unroll") for (int k = 0; k < 2; ++k) dst[m][k] = *(const LAS bf16x8*)(lds + PG8_SA(b, h) + aoff + m * 2048 + k * 1024); } while (0)
; #define PG8_LDB(dst, b, h) do { _Pragma("unroll") for (int n = 0; n < 2; ++n) _Pragma("unroll") for (int k = 0; k < 2; ++k) dst[n][k] = *(const LAS bf16x8*)(lds + PG8_SB(b, h) + boff + n * 2048 + k * 1024); } while (0)
; #define PG8_MMA(ai, bj, At, Bt) do { __builtin_amdgcn_s_setprio(1); _Pragma("unroll") for (int m = 0; m < 4; ++m) _Pragma("unroll") for (int n = 0; n < 2; ++n) _Pragma("unroll") for (int k = 0; k < 2; ++k) \
;         acc[ai][bj][m][n] = __builtin_amdgcn_mfma_f32_16x16x32_bf16(Bt[n][k], At[m][k], acc[ai][bj][m][n], 0, 0, 0); __builtin_amdgcn_s_setprio(0); } while (0)
; #define PG8_BAR __builtin_amdgcn_s_barrier()
; template <class Epi, bool ALIGN_EPI = true, bool SP2 = true>
; DI void gemm_phase(LAS unsigned char* lds, const Gemm g, const StaticOrder& S, const Epi& E) {
;     ...
;             const bool last = (t == nt - 2);
;             const char* a1 = cA + (size_t)(t + 1) * kstep;
;             const char* a2 = last ? nA : cA + (size_t)(t + 2) * kstep; const char* b2 = last ? nB : cB + (size_t)(t + 2) * kstep;
;             const char* a3 = a2 + kstep; const char* b3 = b2 + kstep;
;             if (Epi::MID) { if (t == (nt >> 1)) {
;                 if constexpr (ALIGN_EPI) { if (wr == 0) PG8_BAR; }
;                 E.mid(acc, cur, wr, wc, fr, fq);
;                 if constexpr (ALIGN_EPI) { if (wr == 1) PG8_BAR; } } }
;             if constexpr (SP2) {
;             PG8_LDB(B0, 0, 0); PG8_LDB(B1, 0, 1); PG8_SCHED; PG8_LDA(At, 0, 0); PG8_STAGE(PG8_SA(1, 1), a1 + hstepA, voffA);
;             PG8_WAIT_V(8); PG8_WAIT_L(0); PG8_BAR; PG8_MMA(0, 0, At, B0); PG8_MMA(0, 1, At, B1); PG8_BAR; PG8_SCHED;
;             PG8_LDA(At, 0, 1); PG8_STAGE(PG8_SB(0, 0), b2, voffB); PG8_STAGE(PG8_SB(0, 1), b2 + hstepB, voffB); PG8_STAGE(PG8_SA(0, 0), a2, voffA);
;             PG8_WAIT_V(8); PG8_WAIT_L(0); PG8_BAR; PG8_MMA(1, 0, At, B0); PG8_MMA(1, 1, At, B1); PG8_BAR; PG8_SCHED;
.LBB0_839:
	ds_read_b128 v[140:143], v149
	ds_read_b128 v[152:155], v149 offset:1024
	ds_read_b128 v[156:159], v149 offset:2048
	ds_read_b128 v[160:163], v149 offset:3072
	ds_read_b128 v[164:167], v150
	ds_read_b128 v[168:171], v150 offset:1024
	ds_read_b128 v[172:175], v150 offset:2048
	ds_read_b128 v[176:179], v150 offset:3072
	s_add_u32 s34, s30, 0xfff00080
	s_addc_u32 s35, s31, -1
	s_cmp_eq_u32 s59, 60
	s_cselect_b32 s37, s23, s35
	s_cselect_b32 s36, s50, s34
	s_cselect_b32 s35, s21, s57
	s_cselect_b32 s34, s51, s56
	v_lshl_add_u64 v[144:145], s[30:31], 0, v[132:133]
	s_add_i32 m0, s29, 0xc000
	ds_read_b128 v[180:183], v151
	ds_read_b128 v[184:187], v151 offset:1024
	ds_read_b128 v[188:191], v151 offset:2048
	ds_read_b128 v[192:195], v151 offset:3072
	ds_read_b128 v[196:199], v151 offset:4096
	ds_read_b128 v[200:203], v151 offset:5120
	ds_read_b128 v[204:207], v151 offset:6144
	ds_read_b128 v[208:211], v151 offset:7168
	global_load_lds_dwordx4 v[144:145], off
	v_lshl_add_u64 v[144:145], s[30:31], 0, v[134:135]
	s_add_i32 m0, s29, 0xe000
	s_nop 0
	global_load_lds_dwordx4 v[144:145], off
	s_waitcnt vmcnt(8)
	s_waitcnt lgkmcnt(0)
	s_barrier
	s_waitcnt lgkmcnt(0)
	v_mfma_f32_16x16x32_bf16 v[124:127], v[140:143], v[180:183], v[124:127]
	v_mfma_f32_16x16x32_bf16 v[120:123], v[156:159], v[180:183], v[120:123]
	v_mfma_f32_16x16x32_bf16 v[116:119], v[140:143], v[188:191], v[116:119]
	v_mfma_f32_16x16x32_bf16 v[112:115], v[156:159], v[188:191], v[112:115]
	v_mfma_f32_16x16x32_bf16 v[108:111], v[140:143], v[196:199], v[108:111]
	v_mfma_f32_16x16x32_bf16 v[100:103], v[156:159], v[196:199], v[100:103]
	v_mfma_f32_16x16x32_bf16 v[92:95], v[140:143], v[204:207], v[92:95]
	v_mfma_f32_16x16x32_bf16 v[80:83], v[156:159], v[204:207], v[80:83]
	v_mfma_f32_16x16x32_bf16 v[124:127], v[152:155], v[184:187], v[124:127]
	v_mfma_f32_16x16x32_bf16 v[120:123], v[160:163], v[184:187], v[120:123]
	v_mfma_f32_16x16x32_bf16 v[116:119], v[152:155], v[192:195], v[116:119]
	v_mfma_f32_16x16x32_bf16 v[112:115], v[160:163], v[192:195], v[112:115]
	v_mfma_f32_16x16x32_bf16 v[108:111], v[152:155], v[200:203], v[108:111]
	v_mfma_f32_16x16x32_bf16 v[100:103], v[160:163], v[200:203], v[100:103]
	v_mfma_f32_16x16x32_bf16 v[92:95], v[152:155], v[208:211], v[92:95]
	v_mfma_f32_16x16x32_bf16 v[80:83], v[160:163], v[208:211], v[80:83]
	v_mfma_f32_16x16x32_bf16 v[104:107], v[164:167], v[180:183], v[104:107]
	v_mfma_f32_16x16x32_bf16 v[96:99], v[172:175], v[180:183], v[96:99]
	v_mfma_f32_16x16x32_bf16 v[88:91], v[164:167], v[188:191], v[88:91]
	v_mfma_f32_16x16x32_bf16 v[84:87], v[172:175], v[188:191], v[84:87]
	v_mfma_f32_16x16x32_bf16 v[76:79], v[164:167], v[196:199], v[76:79]
	v_mfma_f32_16x16x32_bf16 v[72:75], v[172:175], v[196:199], v[72:75]
	v_mfma_f32_16x16x32_bf16 v[68:71], v[164:167], v[204:207], v[68:71]
	v_mfma_f32_16x16x32_bf16 v[64:67], v[172:175], v[204:207], v[64:67]
	v_mfma_f32_16x16x32_bf16 v[104:107], v[168:171], v[184:187], v[104:107]
	v_mfma_f32_16x16x32_bf16 v[96:99], v[176:179], v[184:187], v[96:99]
	v_mfma_f32_16x16x32_bf16 v[88:91], v[168:171], v[192:195], v[88:91]
	v_mfma_f32_16x16x32_bf16 v[84:87], v[176:179], v[192:195], v[84:87]
	v_mfma_f32_16x16x32_bf16 v[76:79], v[168:171], v[200:203], v[76:79]
	v_mfma_f32_16x16x32_bf16 v[72:75], v[176:179], v[200:203], v[72:75]
	v_mfma_f32_16x16x32_bf16 v[68:71], v[168:171], v[208:211], v[68:71]
	v_mfma_f32_16x16x32_bf16 v[64:67], v[176:179], v[208:211], v[64:67]
	s_barrier
	s_add_i32 s60, s47, s39
	v_lshl_add_u64 v[144:145], s[34:35], 0, v[128:129]
	s_mov_b32 m0, s60
	ds_read_b128 v[180:183], v151 offset:16384
	ds_read_b128 v[184:187], v151 offset:17408
	ds_read_b128 v[188:191], v151 offset:18432
	ds_read_b128 v[192:195], v151 offset:19456
	ds_read_b128 v[196:199], v151 offset:20480
	ds_read_b128 v[200:203], v151 offset:21504
	ds_read_b128 v[204:207], v151 offset:22528
	ds_read_b128 v[208:211], v151 offset:23552
	global_load_lds_dwordx4 v[144:145], off
	s_add_i32 m0, s60, 0x2000
	s_add_u32 s60, s34, 0x100000
	v_lshl_add_u64 v[212:213], s[34:35], 0, v[130:131]
	s_addc_u32 s61, s35, 0
	s_add_i32 s62, s48, s39
	global_load_lds_dwordx4 v[212:213], off
	v_lshl_add_u64 v[214:215], s[60:61], 0, v[128:129]
	s_mov_b32 m0, s62
	v_lshl_add_u64 v[216:217], s[36:37], 0, v[130:131]
	global_load_lds_dwordx4 v[214:215], off
	v_lshl_add_u64 v[214:215], s[60:61], 0, v[130:131]
	s_add_i32 m0, s62, 0x2000
	s_nop 0
	global_load_lds_dwordx4 v[214:215], off
	v_lshl_add_u64 v[214:215], s[36:37], 0, v[128:129]
	s_mov_b32 m0, s29
	s_nop 0
	global_load_lds_dwordx4 v[214:215], off
	s_mov_b32 m0, s40
	s_nop 0
	global_load_lds_dwordx4 v[216:217], off
	s_waitcnt vmcnt(8)
	s_waitcnt lgkmcnt(0)
	s_barrier
; #define PG8_STAGE(bufoff, gbase, voff) do { _Pragma("unroll") for (int _i = 0; _i < 2; ++_i) \
;         __builtin_amdgcn_global_load_lds((const unsigned*)((const char*)(gbase) + (voff)[_i]), (LAS unsigned*)(lds + (bufoff) + ldsw + _i * 8192), 16, 0, 0); } while (0)
; #define PG8_LDA(dst, b, h) do { _Pragma("unroll") for (int m = 0; m < 4; ++m) _Pragma("unroll") for (int k = 0; k < 2; ++k) dst[m][k] = *(const LAS bf16x8*)(lds + PG8_SA(b, h) + aoff + m * 2048 + k * 1024); } while (0)
; #define PG8_LDB(dst, b, h) do { _Pragma("unroll") for (int n = 0; n < 2; ++n) _Pragma("unroll") for (int k = 0; k < 2; ++k) dst[n][k] = *(const LAS bf16x8*)(lds + PG8_SB(b, h) + boff + n * 2048 + k * 1024); } while (0)
; #define PG8_MMA(ai, bj, At, Bt) do { __builtin_amdgcn_s_setprio(1); _Pragma("unroll") for (int m = 0; m < 4; ++m) _Pragma("unroll") for (int n = 0; n < 2; ++n) _Pragma("unroll") for (int k = 0; k < 2; ++k) \
;         acc[ai][bj][m][n] = __builtin_amdgcn_mfma_f32_16x16x32_bf16(Bt[n][k], At[m][k], acc[ai][bj][m][n], 0, 0, 0); __builtin_amdgcn_s_setprio(0); } while (0)
; #define PG8_WAIT_V(n) asm volatile("s_waitcnt vmcnt(" #n ")" ::: "memory")
; #define PG8_WAIT_L(n) asm volatile("s_waitcnt lgkmcnt(" #n ")" ::: "memory")
; #define PG8_BAR __builtin_amdgcn_s_barrier()
; #define PG8_SCHED __builtin_amdgcn_sched_barrier(0)
; template <class Epi, bool ALIGN_EPI = true, bool SP2 = true>
; DI void gemm_phase(LAS unsigned char* lds, const Gemm g, const StaticOrder& S, const Epi& E) {
;     ...
;             PG8_WAIT_V(8); PG8_WAIT_L(0); PG8_BAR; PG8_MMA(1, 0, At, B0); PG8_MMA(1, 1, At, B1); PG8_BAR; PG8_SCHED;
;             PG8_LDB(B0, 1, 0); PG8_LDB(B1, 1, 1); PG8_SCHED; PG8_LDA(At, 1, 0); PG8_STAGE(PG8_SA(0, 1), a2 + hstepA, voffA);
;             PG8_WAIT_V(8); PG8_WAIT_L(0); PG8_BAR; PG8_MMA(0, 0, At, B0); PG8_MMA(0, 1, At, B1); PG8_BAR; PG8_SCHED;
	s_waitcnt lgkmcnt(0)
	v_mfma_f32_16x16x32_bf16 v[60:63], v[140:143], v[180:183], v[60:63]
	v_mfma_f32_16x16x32_bf16 v[56:59], v[156:159], v[180:183], v[56:59]
	v_mfma_f32_16x16x32_bf16 v[52:55], v[140:143], v[188:191], v[52:55]
	v_mfma_f32_16x16x32_bf16 v[48:51], v[156:159], v[188:191], v[48:51]
	v_mfma_f32_16x16x32_bf16 v[44:47], v[140:143], v[196:199], v[44:47]
	v_mfma_f32_16x16x32_bf16 v[36:39], v[156:159], v[196:199], v[36:39]
	v_mfma_f32_16x16x32_bf16 v[28:31], v[140:143], v[204:207], v[28:31]
	v_mfma_f32_16x16x32_bf16 v[16:19], v[156:159], v[204:207], v[16:19]
	v_mfma_f32_16x16x32_bf16 v[60:63], v[152:155], v[184:187], v[60:63]
	v_mfma_f32_16x16x32_bf16 v[56:59], v[160:163], v[184:187], v[56:59]
	v_mfma_f32_16x16x32_bf16 v[52:55], v[152:155], v[192:195], v[52:55]
	v_mfma_f32_16x16x32_bf16 v[48:51], v[160:163], v[192:195], v[48:51]
	v_mfma_f32_16x16x32_bf16 v[44:47], v[152:155], v[200:203], v[44:47]
	v_mfma_f32_16x16x32_bf16 v[36:39], v[160:163], v[200:203], v[36:39]
	v_mfma_f32_16x16x32_bf16 v[28:31], v[152:155], v[208:211], v[28:31]
	v_mfma_f32_16x16x32_bf16 v[16:19], v[160:163], v[208:211], v[16:19]
	v_mfma_f32_16x16x32_bf16 v[40:43], v[164:167], v[180:183], v[40:43]
	v_mfma_f32_16x16x32_bf16 v[32:35], v[172:175], v[180:183], v[32:35]
	v_mfma_f32_16x16x32_bf16 v[24:27], v[164:167], v[188:191], v[24:27]
	v_mfma_f32_16x16x32_bf16 v[20:23], v[172:175], v[188:191], v[20:23]
	v_mfma_f32_16x16x32_bf16 v[12:15], v[164:167], v[196:199], v[12:15]
	v_mfma_f32_16x16x32_bf16 v[8:11], v[172:175], v[196:199], v[8:11]
	v_mfma_f32_16x16x32_bf16 v[4:7], v[164:167], v[204:207], v[4:7]
	v_mfma_f32_16x16x32_bf16 v[0:3], v[172:175], v[204:207], v[0:3]
	v_mfma_f32_16x16x32_bf16 v[40:43], v[168:171], v[184:187], v[40:43]
	v_mfma_f32_16x16x32_bf16 v[32:35], v[176:179], v[184:187], v[32:35]
	v_mfma_f32_16x16x32_bf16 v[24:27], v[168:171], v[192:195], v[24:27]
	v_mfma_f32_16x16x32_bf16 v[20:23], v[176:179], v[192:195], v[20:23]
	v_mfma_f32_16x16x32_bf16 v[12:15], v[168:171], v[200:203], v[12:15]
	v_mfma_f32_16x16x32_bf16 v[8:11], v[176:179], v[200:203], v[8:11]
	v_mfma_f32_16x16x32_bf16 v[4:7], v[168:171], v[208:211], v[4:7]
	v_mfma_f32_16x16x32_bf16 v[0:3], v[176:179], v[208:211], v[0:3]
	s_barrier
	s_add_i32 s60, 0, 0x18000
	s_add_i32 s61, 0, 0x1c000
	v_add_u32_e32 v160, s60, v147
	v_add_u32_e32 v176, s61, v147
	ds_read_b128 v[140:143], v160
	ds_read_b128 v[152:155], v160 offset:1024
	ds_read_b128 v[156:159], v160 offset:2048
	ds_read_b128 v[160:163], v160 offset:3072
	ds_read_b128 v[164:167], v176
	ds_read_b128 v[168:171], v176 offset:1024
	ds_read_b128 v[172:175], v176 offset:2048
	ds_read_b128 v[176:179], v176 offset:3072
	s_add_u32 s36, s36, 0x100000
	s_addc_u32 s37, s37, 0
	s_mov_b32 m0, s41
	v_lshl_add_u64 v[218:219], s[36:37], 0, v[128:129]
	ds_read_b128 v[180:183], v151 offset:32768
	ds_read_b128 v[184:187], v151 offset:33792
	ds_read_b128 v[188:191], v151 offset:34816
	ds_read_b128 v[192:195], v151 offset:35840
	ds_read_b128 v[196:199], v151 offset:36864
	ds_read_b128 v[200:203], v151 offset:37888
	ds_read_b128 v[204:207], v151 offset:38912
	ds_read_b128 v[208:211], v151 offset:39936
	global_load_lds_dwordx4 v[218:219], off
	v_lshl_add_u64 v[218:219], s[36:37], 0, v[130:131]
	s_mov_b32 m0, s42
	s_nop 0
	global_load_lds_dwordx4 v[218:219], off
	s_waitcnt vmcnt(8)
	s_waitcnt lgkmcnt(0)
	s_barrier
	s_waitcnt lgkmcnt(0)
	v_mfma_f32_16x16x32_bf16 v[124:127], v[140:143], v[180:183], v[124:127]
	v_mfma_f32_16x16x32_bf16 v[120:123], v[156:159], v[180:183], v[120:123]
	v_mfma_f32_16x16x32_bf16 v[116:119], v[140:143], v[188:191], v[116:119]
	v_mfma_f32_16x16x32_bf16 v[112:115], v[156:159], v[188:191], v[112:115]
	v_mfma_f32_16x16x32_bf16 v[108:111], v[140:143], v[196:199], v[108:111]
	v_mfma_f32_16x16x32_bf16 v[100:103], v[156:159], v[196:199], v[100:103]
	v_mfma_f32_16x16x32_bf16 v[92:95], v[140:143], v[204:207], v[92:95]
	v_mfma_f32_16x16x32_bf16 v[80:83], v[156:159], v[204:207], v[80:83]
	v_mfma_f32_16x16x32_bf16 v[124:127], v[152:155], v[184:187], v[124:127]
	v_mfma_f32_16x16x32_bf16 v[120:123], v[160:163], v[184:187], v[120:123]
	v_mfma_f32_16x16x32_bf16 v[116:119], v[152:155], v[192:195], v[116:119]
	v_mfma_f32_16x16x32_bf16 v[112:115], v[160:163], v[192:195], v[112:115]
	v_mfma_f32_16x16x32_bf16 v[108:111], v[152:155], v[200:203], v[108:111]
	v_mfma_f32_16x16x32_bf16 v[100:103], v[160:163], v[200:203], v[100:103]
	v_mfma_f32_16x16x32_bf16 v[92:95], v[152:155], v[208:211], v[92:95]
	v_mfma_f32_16x16x32_bf16 v[80:83], v[160:163], v[208:211], v[80:83]
	v_mfma_f32_16x16x32_bf16 v[104:107], v[164:167], v[180:183], v[104:107]
	v_mfma_f32_16x16x32_bf16 v[96:99], v[172:175], v[180:183], v[96:99]
	v_mfma_f32_16x16x32_bf16 v[88:91], v[164:167], v[188:191], v[88:91]
	v_mfma_f32_16x16x32_bf16 v[84:87], v[172:175], v[188:191], v[84:87]
	v_mfma_f32_16x16x32_bf16 v[76:79], v[164:167], v[196:199], v[76:79]
	v_mfma_f32_16x16x32_bf16 v[72:75], v[172:175], v[196:199], v[72:75]
	v_mfma_f32_16x16x32_bf16 v[68:71], v[164:167], v[204:207], v[68:71]
	v_mfma_f32_16x16x32_bf16 v[64:67], v[172:175], v[204:207], v[64:67]
	v_mfma_f32_16x16x32_bf16 v[104:107], v[168:171], v[184:187], v[104:107]
	v_mfma_f32_16x16x32_bf16 v[96:99], v[176:179], v[184:187], v[96:99]
	v_mfma_f32_16x16x32_bf16 v[88:91], v[168:171], v[192:195], v[88:91]
	v_mfma_f32_16x16x32_bf16 v[84:87], v[176:179], v[192:195], v[84:87]
	v_mfma_f32_16x16x32_bf16 v[76:79], v[168:171], v[200:203], v[76:79]
	v_mfma_f32_16x16x32_bf16 v[72:75], v[176:179], v[200:203], v[72:75]
	v_mfma_f32_16x16x32_bf16 v[68:71], v[168:171], v[208:211], v[68:71]
	v_mfma_f32_16x16x32_bf16 v[64:67], v[176:179], v[208:211], v[64:67]
	s_barrier
; #define PG8_STAGE(bufoff, gbase, voff) do { _Pragma("unroll") for (int _i = 0; _i < 2; ++_i) \
;         __builtin_amdgcn_global_load_lds((const unsigned*)((const char*)(gbase) + (voff)[_i]), (LAS unsigned*)(lds + (bufoff) + ldsw + _i * 8192), 16, 0, 0); } while (0)
; #define PG8_LDA(dst, b, h) do { _Pragma("unroll") for (int m = 0; m < 4; ++m) _Pragma("unroll") for (int k = 0; k < 2; ++k) dst[m][k] = *(const LAS bf16x8*)(lds + PG8_SA(b, h) + aoff + m * 2048 + k * 1024); } while (0)
; #define PG8_MMA(ai, bj, At, Bt) do { __builtin_amdgcn_s_setprio(1); _Pragma("unroll") for (int m = 0; m < 4; ++m) _Pragma("unroll") for (int n = 0; n < 2; ++n) _Pragma("unroll") for (int k = 0; k < 2; ++k) \
;         acc[ai][bj][m][n] = __builtin_amdgcn_mfma_f32_16x16x32_bf16(Bt[n][k], At[m][k], acc[ai][bj][m][n], 0, 0, 0); __builtin_amdgcn_s_setprio(0); } while (0)
; #define PG8_WAIT_V(n) asm volatile("s_waitcnt vmcnt(" #n ")" ::: "memory")
; #define PG8_WAIT_L(n) asm volatile("s_waitcnt lgkmcnt(" #n ")" ::: "memory")
; #define PG8_BAR __builtin_amdgcn_s_barrier()
; #define PG8_SCHED __builtin_amdgcn_sched_barrier(0)
; template <class Epi, bool ALIGN_EPI = true, bool SP2 = true>
; DI void gemm_phase(LAS unsigned char* lds, const Gemm g, const StaticOrder& S, const Epi& E) {
;     ...
;             PG8_LDA(At, 1, 1); PG8_STAGE(PG8_SB(1, 0), b3, voffB); PG8_STAGE(PG8_SB(1, 1), b3 + hstepB, voffB); PG8_STAGE(PG8_SA(1, 0), a3, voffA);
;             PG8_WAIT_V(8); PG8_WAIT_L(0); PG8_BAR; PG8_MMA(1, 0, At, B0); PG8_MMA(1, 1, At, B1); PG8_BAR; PG8_SCHED;
;     ...
;         if constexpr (ALIGN_EPI) { if (wr == 0) PG8_BAR; }
	s_add_i32 s36, s60, s39
	v_lshl_add_u64 v[144:145], v[144:145], 0, s[6:7]
	s_mov_b32 m0, s36
	ds_read_b128 v[180:183], v151 offset:49152
	ds_read_b128 v[184:187], v151 offset:50176
	ds_read_b128 v[188:191], v151 offset:51200
	ds_read_b128 v[192:195], v151 offset:52224
	ds_read_b128 v[196:199], v151 offset:53248
	ds_read_b128 v[200:203], v151 offset:54272
	ds_read_b128 v[204:207], v151 offset:55296
	ds_read_b128 v[208:211], v151 offset:56320
	global_load_lds_dwordx4 v[144:145], off
	s_add_i32 m0, s36, 0x2000
	s_add_u32 s34, s34, 0x100080
	v_lshl_add_u64 v[144:145], v[212:213], 0, s[6:7]
	s_addc_u32 s35, s35, 0
	s_add_i32 s36, s61, s39
	global_load_lds_dwordx4 v[144:145], off
	v_lshl_add_u64 v[144:145], s[34:35], 0, v[128:129]
	s_mov_b32 m0, s36
	s_nop 0
	global_load_lds_dwordx4 v[144:145], off
	v_lshl_add_u64 v[144:145], s[34:35], 0, v[130:131]
	s_add_i32 m0, s36, 0x2000
	s_nop 0
	global_load_lds_dwordx4 v[144:145], off
	v_lshl_add_u64 v[144:145], v[214:215], 0, s[6:7]
	s_mov_b32 m0, s44
	s_nop 0
	global_load_lds_dwordx4 v[144:145], off
	v_lshl_add_u64 v[144:145], v[216:217], 0, s[6:7]
	s_mov_b32 m0, s45
	s_nop 0
	global_load_lds_dwordx4 v[144:145], off
	s_waitcnt vmcnt(8)
	s_waitcnt lgkmcnt(0)
	s_barrier
	s_waitcnt lgkmcnt(0)
	v_mfma_f32_16x16x32_bf16 v[60:63], v[140:143], v[180:183], v[60:63]
	v_mfma_f32_16x16x32_bf16 v[56:59], v[156:159], v[180:183], v[56:59]
	v_mfma_f32_16x16x32_bf16 v[52:55], v[140:143], v[188:191], v[52:55]
	v_mfma_f32_16x16x32_bf16 v[48:51], v[156:159], v[188:191], v[48:51]
	v_mfma_f32_16x16x32_bf16 v[44:47], v[140:143], v[196:199], v[44:47]
	v_mfma_f32_16x16x32_bf16 v[36:39], v[156:159], v[196:199], v[36:39]
	v_mfma_f32_16x16x32_bf16 v[28:31], v[140:143], v[204:207], v[28:31]
	v_mfma_f32_16x16x32_bf16 v[16:19], v[156:159], v[204:207], v[16:19]
	v_mfma_f32_16x16x32_bf16 v[60:63], v[152:155], v[184:187], v[60:63]
	v_mfma_f32_16x16x32_bf16 v[56:59], v[160:163], v[184:187], v[56:59]
	v_mfma_f32_16x16x32_bf16 v[52:55], v[152:155], v[192:195], v[52:55]
	v_mfma_f32_16x16x32_bf16 v[48:51], v[160:163], v[192:195], v[48:51]
	v_mfma_f32_16x16x32_bf16 v[44:47], v[152:155], v[200:203], v[44:47]
	v_mfma_f32_16x16x32_bf16 v[36:39], v[160:163], v[200:203], v[36:39]
	v_mfma_f32_16x16x32_bf16 v[28:31], v[152:155], v[208:211], v[28:31]
	v_mfma_f32_16x16x32_bf16 v[16:19], v[160:163], v[208:211], v[16:19]
	v_mfma_f32_16x16x32_bf16 v[40:43], v[164:167], v[180:183], v[40:43]
	v_mfma_f32_16x16x32_bf16 v[32:35], v[172:175], v[180:183], v[32:35]
	v_mfma_f32_16x16x32_bf16 v[24:27], v[164:167], v[188:191], v[24:27]
	v_mfma_f32_16x16x32_bf16 v[20:23], v[172:175], v[188:191], v[20:23]
	v_mfma_f32_16x16x32_bf16 v[12:15], v[164:167], v[196:199], v[12:15]
	v_mfma_f32_16x16x32_bf16 v[8:11], v[172:175], v[196:199], v[8:11]
	v_mfma_f32_16x16x32_bf16 v[4:7], v[164:167], v[204:207], v[4:7]
	v_mfma_f32_16x16x32_bf16 v[0:3], v[172:175], v[204:207], v[0:3]
	v_mfma_f32_16x16x32_bf16 v[40:43], v[168:171], v[184:187], v[40:43]
	v_mfma_f32_16x16x32_bf16 v[32:35], v[176:179], v[184:187], v[32:35]
	v_mfma_f32_16x16x32_bf16 v[24:27], v[168:171], v[192:195], v[24:27]
	v_mfma_f32_16x16x32_bf16 v[20:23], v[176:179], v[192:195], v[20:23]
	v_mfma_f32_16x16x32_bf16 v[12:15], v[168:171], v[200:203], v[12:15]
	v_mfma_f32_16x16x32_bf16 v[8:11], v[176:179], v[200:203], v[8:11]
	v_mfma_f32_16x16x32_bf16 v[4:7], v[168:171], v[208:211], v[4:7]
	v_mfma_f32_16x16x32_bf16 v[0:3], v[176:179], v[208:211], v[0:3]
	s_barrier
	s_add_i32 s59, s59, 2
	s_add_u32 s30, s30, 0x100
	s_addc_u32 s31, s31, 0
	s_add_u32 s56, s56, 0x100
	s_addc_u32 s57, s57, 0
	s_cmp_gt_u32 s59, 61
	s_cbranch_scc0 .LBB0_839
	s_and_b64 vcc, exec, s[8:9]
	s_cbranch_vccz .LBB0_842
	s_barrier
